# speedup vs baseline: 1.0595x; 1.0122x over previous
; __device__ __forceinline__ void wkv_phase(const WkvT& W, unsigned char* lds) {
;     ...
;                 const float* pp = sP + bo + jj * 12;
;                 const float* pv = sV + bi * 512 + il;
;                 f32x4 nA = *(const f32x4*)pp, nB = *(const f32x4*)(pp + 4); f32x2 nr = *(const f32x2*)(pp + 8); float nv = pv[0];
;                 float yk0 = 0.f, yk1 = 0.f, ep = 0.f;
;                 const bool oddrow = (lane & 16) != 0;
; #pragma unroll
;                 for (int t = 0; t < 32; ++t) {
;                     const f32x2 a2 = {nA[0], nA[1]}, w2 = {nA[2], nA[3]}, b2 = {nB[0], nB[1]}, k2 = {nB[2], nB[3]}, r2 = nr; const float v = nv;
;                     if (t + 1 < 32) { nA = *(const f32x4*)(pp + (t + 1) * 384); nB = *(const f32x4*)(pp + (t + 1) * 384 + 4); nr = *(const f32x2*)(pp + (t + 1) * 384 + 8); nv = pv[(t + 1) * 16]; }
;                     float S0 = S.x, S1 = S.y;
;                     float d = S0 * a2.x; d = __builtin_fmaf(S1, a2.y, d);
;                     float t0 = S0 * w2.x; t0 = __builtin_fmaf(v, k2.x, t0); asm volatile("" : "+v"(t0));
;                     float t1 = S1 * w2.y; t1 = __builtin_fmaf(v, k2.y, t1); asm volatile("" : "+v"(t1));
;                     float yprev; const float sa = wkv_reduce(d, ep, yprev);
;                     S0 = __builtin_fmaf(sa, b2.x, t0); asm volatile("" : "+v"(S0));
;                     S1 = __builtin_fmaf(sa, b2.y, t1); asm volatile("" : "+v"(S1));
;                     ep = S0 * r2.x; ep = __builtin_fmaf(S1, r2.y, ep);
;                     S.x = S0; S.y = S1;
;                     if (t >= 1) { const bool hit = oddrow && ((lane & 15) == ((t - 1) & 15)); if (t <= 16) yk0 = hit ? yprev : yk0; else yk1 = hit ? yprev : yk1; }
;                 }
.Lwkv4_b1_entry:
	s_bitcmp1_b32 s99, 8
	s_cbranch_scc1 .Lwkv4_b1_skip
	ds_read_b128 v[190:193], v182
	ds_read_b128 v[194:197], v182 offset:16
	ds_read_b64 v[228:229], v182 offset:32
	ds_read_b128 v[198:201], v183
	ds_read_b128 v[202:205], v183 offset:16
	ds_read_b64 v[230:231], v183 offset:32
	ds_read_b32 v240, v186 offset:0
	ds_read_b128 v[206:209], v182 offset:1536
	ds_read_b128 v[210:213], v182 offset:1552
	ds_read_b64 v[232:233], v182 offset:1568
	ds_read_b128 v[214:217], v183 offset:1536
	ds_read_b128 v[218:221], v183 offset:1552
	ds_read_b64 v[234:235], v183 offset:1568
	ds_read_b32 v241, v186 offset:64
	s_waitcnt lgkmcnt(7)
	v_pk_mul_f32 v[150:151], v[142:143], v[190:191]
	v_pk_fma_f32 v[150:151], v[144:145], v[198:199], v[150:151]
	v_pk_mul_f32 v[146:147], v[142:143], v[192:193]
	v_add_f32_e32 v154, v150, v151
	v_pk_mul_f32 v[148:149], v[144:145], v[200:201]
	v_pk_fma_f32 v[146:147], v[240:241], v[196:197], v[146:147] op_sel:[0,0,0] op_sel_hi:[0,1,1]
	v_add_f32_dpp v154, v154, v154 quad_perm:[1,0,3,2] row_mask:0xf bank_mask:0xf bound_ctrl:1
	v_pk_fma_f32 v[148:149], v[240:241], v[204:205], v[148:149] op_sel:[0,0,0] op_sel_hi:[0,1,1]
	s_nop 0
	v_add_f32_dpp v154, v154, v154 quad_perm:[2,3,0,1] row_mask:0xf bank_mask:0xf bound_ctrl:1
	ds_read_b128 v[126:129], v182 offset:3072
	ds_read_b128 v[130:133], v182 offset:3088
	v_add_f32_dpp v154, v154, v154 row_half_mirror row_mask:0xf bank_mask:0xf bound_ctrl:1
	ds_read_b64 v[236:237], v182 offset:3104
	ds_read_b128 v[134:137], v183 offset:3072
	v_add_f32_dpp v154, v154, v154 row_mirror row_mask:0xf bank_mask:0xf bound_ctrl:1
	v_pk_fma_f32 v[146:147], v[154:155], v[194:195], v[146:147] op_sel_hi:[0,1,1]
	v_pk_fma_f32 v[148:149], v[154:155], v[202:203], v[148:149] op_sel_hi:[0,1,1]
	ds_read_b128 v[222:225], v183 offset:3088
	ds_read_b64 v[238:239], v183 offset:3104
	ds_read_b32 v242, v186 offset:128
	s_waitcnt lgkmcnt(7)
	v_pk_mul_f32 v[150:151], v[146:147], v[206:207]
	v_pk_fma_f32 v[150:151], v[148:149], v[214:215], v[150:151]
	v_pk_mul_f32 v[152:153], v[146:147], v[228:229]
	v_add_f32_e32 v154, v150, v151
	v_pk_fma_f32 v[152:153], v[148:149], v[230:231], v[152:153]
	v_pk_mul_f32 v[142:143], v[146:147], v[208:209]
	v_add_f32_dpp v154, v154, v154 quad_perm:[1,0,3,2] row_mask:0xf bank_mask:0xf bound_ctrl:1
	v_pk_mul_f32 v[144:145], v[148:149], v[216:217]
	v_add_f32_e32 v156, v152, v153
	v_add_f32_dpp v154, v154, v154 quad_perm:[2,3,0,1] row_mask:0xf bank_mask:0xf bound_ctrl:1
	v_pk_fma_f32 v[142:143], v[240:241], v[212:213], v[142:143] op_sel:[1,0,0] op_sel_hi:[1,1,1]
	v_pk_fma_f32 v[144:145], v[240:241], v[220:221], v[144:145] op_sel:[1,0,0] op_sel_hi:[1,1,1]
	v_add_f32_dpp v154, v154, v154 row_half_mirror row_mask:0xf bank_mask:0xf bound_ctrl:1
	ds_read_b128 v[190:193], v182 offset:4608
	ds_read_b128 v[194:197], v182 offset:4624
	v_add_f32_dpp v154, v154, v154 row_mirror row_mask:0xf bank_mask:0xf bound_ctrl:1
	ds_read_b64 v[228:229], v182 offset:4640
	ds_read_b128 v[198:201], v183 offset:4608
	v_pk_fma_f32 v[142:143], v[154:155], v[210:211], v[142:143] op_sel_hi:[0,1,1]
	v_pk_fma_f32 v[144:145], v[154:155], v[218:219], v[144:145] op_sel_hi:[0,1,1]
	ds_read_b128 v[202:205], v183 offset:4624
	ds_read_b64 v[230:231], v183 offset:4640
	ds_read_b32 v240, v186 offset:192
	s_waitcnt lgkmcnt(7)
	v_pk_mul_f32 v[150:151], v[142:143], v[126:127]
	v_pk_fma_f32 v[150:151], v[144:145], v[134:135], v[150:151]
	v_pk_mul_f32 v[152:153], v[142:143], v[232:233]
	v_add_f32_e32 v154, v150, v151
	v_pk_fma_f32 v[152:153], v[144:145], v[234:235], v[152:153]
	v_pk_mul_f32 v[146:147], v[142:143], v[128:129]
	v_add_f32_dpp v154, v154, v154 quad_perm:[1,0,3,2] row_mask:0xf bank_mask:0xf bound_ctrl:1
	v_pk_mul_f32 v[148:149], v[144:145], v[136:137]
	v_add_f32_e32 v157, v152, v153
	v_add_f32_dpp v154, v154, v154 quad_perm:[2,3,0,1] row_mask:0xf bank_mask:0xf bound_ctrl:1
	v_pk_fma_f32 v[146:147], v[242:243], v[132:133], v[146:147] op_sel:[0,0,0] op_sel_hi:[0,1,1]
	v_pk_fma_f32 v[148:149], v[242:243], v[224:225], v[148:149] op_sel:[0,0,0] op_sel_hi:[0,1,1]
	v_add_f32_dpp v154, v154, v154 row_half_mirror row_mask:0xf bank_mask:0xf bound_ctrl:1
	ds_read_b128 v[206:209], v182 offset:6144
	ds_read_b128 v[210:213], v182 offset:6160
	v_add_f32_dpp v154, v154, v154 row_mirror row_mask:0xf bank_mask:0xf bound_ctrl:1
	ds_read_b64 v[232:233], v182 offset:6176
	ds_read_b128 v[214:217], v183 offset:6144
	v_pk_fma_f32 v[146:147], v[154:155], v[130:131], v[146:147] op_sel_hi:[0,1,1]
	v_pk_fma_f32 v[148:149], v[154:155], v[222:223], v[148:149] op_sel_hi:[0,1,1]
	ds_read_b128 v[218:221], v183 offset:6160
	ds_read_b64 v[234:235], v183 offset:6176
	ds_read_b32 v241, v186 offset:256
	s_waitcnt lgkmcnt(7)
	v_pk_mul_f32 v[150:151], v[146:147], v[190:191]
	v_pk_fma_f32 v[150:151], v[148:149], v[198:199], v[150:151]
	v_pk_mul_f32 v[152:153], v[146:147], v[236:237]
	v_add_f32_e32 v154, v150, v151
	v_pk_fma_f32 v[152:153], v[148:149], v[238:239], v[152:153]
	v_pk_mul_f32 v[142:143], v[146:147], v[192:193]
	v_add_f32_dpp v154, v154, v154 quad_perm:[1,0,3,2] row_mask:0xf bank_mask:0xf bound_ctrl:1
	v_pk_mul_f32 v[144:145], v[148:149], v[200:201]
	v_add_f32_e32 v158, v152, v153
	v_add_f32_dpp v154, v154, v154 quad_perm:[2,3,0,1] row_mask:0xf bank_mask:0xf bound_ctrl:1
	v_pk_fma_f32 v[142:143], v[240:241], v[196:197], v[142:143] op_sel:[0,0,0] op_sel_hi:[0,1,1]
	v_pk_fma_f32 v[144:145], v[240:241], v[204:205], v[144:145] op_sel:[0,0,0] op_sel_hi:[0,1,1]
	v_add_f32_dpp v154, v154, v154 row_half_mirror row_mask:0xf bank_mask:0xf bound_ctrl:1
	ds_read_b128 v[126:129], v182 offset:7680
	ds_read_b128 v[130:133], v182 offset:7696
	v_add_f32_dpp v154, v154, v154 row_mirror row_mask:0xf bank_mask:0xf bound_ctrl:1
	ds_read_b64 v[236:237], v182 offset:7712
	ds_read_b128 v[134:137], v183 offset:7680
	v_pk_fma_f32 v[142:143], v[154:155], v[194:195], v[142:143] op_sel_hi:[0,1,1]
	v_pk_fma_f32 v[144:145], v[154:155], v[202:203], v[144:145] op_sel_hi:[0,1,1]
	ds_read_b128 v[222:225], v183 offset:7696
	ds_read_b64 v[238:239], v183 offset:7712
	ds_read_b32 v242, v186 offset:320
	s_waitcnt lgkmcnt(7)
; __device__ __forceinline__ void wkv_phase(const WkvT& W, unsigned char* lds) {
;     ...
;                 for (int t = 0; t < 32; ++t) {
;                     const f32x2 a2 = {nA[0], nA[1]}, w2 = {nA[2], nA[3]}, b2 = {nB[0], nB[1]}, k2 = {nB[2], nB[3]}, r2 = nr; const float v = nv;
;                     if (t + 1 < 32) { nA = *(const f32x4*)(pp + (t + 1) * 384); nB = *(const f32x4*)(pp + (t + 1) * 384 + 4); nr = *(const f32x2*)(pp + (t + 1) * 384 + 8); nv = pv[(t + 1) * 16]; }
;                     float S0 = S.x, S1 = S.y;
;                     float d = S0 * a2.x; d = __builtin_fmaf(S1, a2.y, d);
;                     float t0 = S0 * w2.x; t0 = __builtin_fmaf(v, k2.x, t0); asm volatile("" : "+v"(t0));
;                     float t1 = S1 * w2.y; t1 = __builtin_fmaf(v, k2.y, t1); asm volatile("" : "+v"(t1));
;                     float yprev; const float sa = wkv_reduce(d, ep, yprev);
;                     S0 = __builtin_fmaf(sa, b2.x, t0); asm volatile("" : "+v"(S0));
;                     S1 = __builtin_fmaf(sa, b2.y, t1); asm volatile("" : "+v"(S1));
;                     ep = S0 * r2.x; ep = __builtin_fmaf(S1, r2.y, ep);
;                     S.x = S0; S.y = S1;
;                     if (t >= 1) { const bool hit = oddrow && ((lane & 15) == ((t - 1) & 15)); if (t <= 16) yk0 = hit ? yprev : yk0; else yk1 = hit ? yprev : yk1; }
;                 }
	v_pk_mul_f32 v[150:151], v[142:143], v[206:207]
	v_pk_fma_f32 v[150:151], v[144:145], v[214:215], v[150:151]
	v_pk_mul_f32 v[152:153], v[142:143], v[228:229]
	v_add_f32_e32 v154, v150, v151
	v_pk_fma_f32 v[152:153], v[144:145], v[230:231], v[152:153]
	v_pk_mul_f32 v[146:147], v[142:143], v[208:209]
	v_add_f32_dpp v154, v154, v154 quad_perm:[1,0,3,2] row_mask:0xf bank_mask:0xf bound_ctrl:1
	v_pk_mul_f32 v[148:149], v[144:145], v[216:217]
	v_add_f32_e32 v159, v152, v153
	v_add_f32_dpp v154, v154, v154 quad_perm:[2,3,0,1] row_mask:0xf bank_mask:0xf bound_ctrl:1
	v_pk_fma_f32 v[146:147], v[240:241], v[212:213], v[146:147] op_sel:[1,0,0] op_sel_hi:[1,1,1]
	v_pk_fma_f32 v[148:149], v[240:241], v[220:221], v[148:149] op_sel:[1,0,0] op_sel_hi:[1,1,1]
	v_add_f32_dpp v154, v154, v154 row_half_mirror row_mask:0xf bank_mask:0xf bound_ctrl:1
	ds_read_b128 v[190:193], v182 offset:9216
	ds_read_b128 v[194:197], v182 offset:9232
	v_add_f32_dpp v154, v154, v154 row_mirror row_mask:0xf bank_mask:0xf bound_ctrl:1
	ds_read_b64 v[228:229], v182 offset:9248
	ds_read_b128 v[198:201], v183 offset:9216
	v_pk_fma_f32 v[146:147], v[154:155], v[210:211], v[146:147] op_sel_hi:[0,1,1]
	v_pk_fma_f32 v[148:149], v[154:155], v[218:219], v[148:149] op_sel_hi:[0,1,1]
	ds_read_b128 v[202:205], v183 offset:9232
	ds_read_b64 v[230:231], v183 offset:9248
	ds_read_b32 v240, v186 offset:384
	s_waitcnt lgkmcnt(7)
	v_pk_mul_f32 v[150:151], v[146:147], v[126:127]
	v_pk_fma_f32 v[150:151], v[148:149], v[134:135], v[150:151]
	v_pk_mul_f32 v[152:153], v[146:147], v[232:233]
	v_add_f32_e32 v154, v150, v151
	v_pk_fma_f32 v[152:153], v[148:149], v[234:235], v[152:153]
	v_pk_mul_f32 v[142:143], v[146:147], v[128:129]
	v_add_f32_dpp v154, v154, v154 quad_perm:[1,0,3,2] row_mask:0xf bank_mask:0xf bound_ctrl:1
	v_pk_mul_f32 v[144:145], v[148:149], v[136:137]
	v_add_f32_e32 v160, v152, v153
	v_add_f32_dpp v154, v154, v154 quad_perm:[2,3,0,1] row_mask:0xf bank_mask:0xf bound_ctrl:1
	v_pk_fma_f32 v[142:143], v[242:243], v[132:133], v[142:143] op_sel:[0,0,0] op_sel_hi:[0,1,1]
	v_pk_fma_f32 v[144:145], v[242:243], v[224:225], v[144:145] op_sel:[0,0,0] op_sel_hi:[0,1,1]
	v_add_f32_dpp v154, v154, v154 row_half_mirror row_mask:0xf bank_mask:0xf bound_ctrl:1
	ds_read_b128 v[206:209], v182 offset:10752
	ds_read_b128 v[210:213], v182 offset:10768
	v_add_f32_dpp v154, v154, v154 row_mirror row_mask:0xf bank_mask:0xf bound_ctrl:1
	ds_read_b64 v[232:233], v182 offset:10784
	ds_read_b128 v[214:217], v183 offset:10752
	v_pk_fma_f32 v[142:143], v[154:155], v[130:131], v[142:143] op_sel_hi:[0,1,1]
	v_pk_fma_f32 v[144:145], v[154:155], v[222:223], v[144:145] op_sel_hi:[0,1,1]
	ds_read_b128 v[218:221], v183 offset:10768
	ds_read_b64 v[234:235], v183 offset:10784
	ds_read_b32 v241, v186 offset:448
	s_waitcnt lgkmcnt(7)
	v_pk_mul_f32 v[150:151], v[142:143], v[190:191]
	v_pk_fma_f32 v[150:151], v[144:145], v[198:199], v[150:151]
	v_pk_mul_f32 v[152:153], v[142:143], v[236:237]
	v_add_f32_e32 v154, v150, v151
	v_pk_fma_f32 v[152:153], v[144:145], v[238:239], v[152:153]
	v_pk_mul_f32 v[146:147], v[142:143], v[192:193]
	v_add_f32_dpp v154, v154, v154 quad_perm:[1,0,3,2] row_mask:0xf bank_mask:0xf bound_ctrl:1
	v_pk_mul_f32 v[148:149], v[144:145], v[200:201]
	v_add_f32_e32 v161, v152, v153
	v_add_f32_dpp v154, v154, v154 quad_perm:[2,3,0,1] row_mask:0xf bank_mask:0xf bound_ctrl:1
	v_pk_fma_f32 v[146:147], v[240:241], v[196:197], v[146:147] op_sel:[0,0,0] op_sel_hi:[0,1,1]
	v_pk_fma_f32 v[148:149], v[240:241], v[204:205], v[148:149] op_sel:[0,0,0] op_sel_hi:[0,1,1]
	v_add_f32_dpp v154, v154, v154 row_half_mirror row_mask:0xf bank_mask:0xf bound_ctrl:1
	ds_read_b128 v[126:129], v182 offset:12288
	ds_read_b128 v[130:133], v182 offset:12304
	v_add_f32_dpp v154, v154, v154 row_mirror row_mask:0xf bank_mask:0xf bound_ctrl:1
	ds_read_b64 v[236:237], v182 offset:12320
	ds_read_b128 v[134:137], v183 offset:12288
	v_pk_fma_f32 v[146:147], v[154:155], v[194:195], v[146:147] op_sel_hi:[0,1,1]
	v_pk_fma_f32 v[148:149], v[154:155], v[202:203], v[148:149] op_sel_hi:[0,1,1]
	ds_read_b128 v[222:225], v183 offset:12304
	ds_read_b64 v[238:239], v183 offset:12320
	ds_read_b32 v242, v186 offset:512
	s_waitcnt lgkmcnt(7)
	v_pk_mul_f32 v[150:151], v[146:147], v[206:207]
	v_pk_fma_f32 v[150:151], v[148:149], v[214:215], v[150:151]
	v_pk_mul_f32 v[152:153], v[146:147], v[228:229]
	v_add_f32_e32 v154, v150, v151
	v_pk_fma_f32 v[152:153], v[148:149], v[230:231], v[152:153]
	v_pk_mul_f32 v[142:143], v[146:147], v[208:209]
	v_add_f32_dpp v154, v154, v154 quad_perm:[1,0,3,2] row_mask:0xf bank_mask:0xf bound_ctrl:1
	v_pk_mul_f32 v[144:145], v[148:149], v[216:217]
	v_add_f32_e32 v162, v152, v153
	v_add_f32_dpp v154, v154, v154 quad_perm:[2,3,0,1] row_mask:0xf bank_mask:0xf bound_ctrl:1
	v_pk_fma_f32 v[142:143], v[240:241], v[212:213], v[142:143] op_sel:[1,0,0] op_sel_hi:[1,1,1]
	v_pk_fma_f32 v[144:145], v[240:241], v[220:221], v[144:145] op_sel:[1,0,0] op_sel_hi:[1,1,1]
	v_add_f32_dpp v154, v154, v154 row_half_mirror row_mask:0xf bank_mask:0xf bound_ctrl:1
	ds_read_b128 v[190:193], v182 offset:13824
	ds_read_b128 v[194:197], v182 offset:13840
	v_add_f32_dpp v154, v154, v154 row_mirror row_mask:0xf bank_mask:0xf bound_ctrl:1
	ds_read_b64 v[228:229], v182 offset:13856
	ds_read_b128 v[198:201], v183 offset:13824
	v_pk_fma_f32 v[142:143], v[154:155], v[210:211], v[142:143] op_sel_hi:[0,1,1]
	v_pk_fma_f32 v[144:145], v[154:155], v[218:219], v[144:145] op_sel_hi:[0,1,1]
	ds_read_b128 v[202:205], v183 offset:13840
	ds_read_b64 v[230:231], v183 offset:13856
	ds_read_b32 v240, v186 offset:576
	s_waitcnt lgkmcnt(7)
; __device__ __forceinline__ void wkv_phase(const WkvT& W, unsigned char* lds) {
;     ...
;                 for (int t = 0; t < 32; ++t) {
;                     const f32x2 a2 = {nA[0], nA[1]}, w2 = {nA[2], nA[3]}, b2 = {nB[0], nB[1]}, k2 = {nB[2], nB[3]}, r2 = nr; const float v = nv;
;                     if (t + 1 < 32) { nA = *(const f32x4*)(pp + (t + 1) * 384); nB = *(const f32x4*)(pp + (t + 1) * 384 + 4); nr = *(const f32x2*)(pp + (t + 1) * 384 + 8); nv = pv[(t + 1) * 16]; }
;                     float S0 = S.x, S1 = S.y;
;                     float d = S0 * a2.x; d = __builtin_fmaf(S1, a2.y, d);
;                     float t0 = S0 * w2.x; t0 = __builtin_fmaf(v, k2.x, t0); asm volatile("" : "+v"(t0));
;                     float t1 = S1 * w2.y; t1 = __builtin_fmaf(v, k2.y, t1); asm volatile("" : "+v"(t1));
;                     float yprev; const float sa = wkv_reduce(d, ep, yprev);
;                     S0 = __builtin_fmaf(sa, b2.x, t0); asm volatile("" : "+v"(S0));
;                     S1 = __builtin_fmaf(sa, b2.y, t1); asm volatile("" : "+v"(S1));
;                     ep = S0 * r2.x; ep = __builtin_fmaf(S1, r2.y, ep);
;                     S.x = S0; S.y = S1;
;                     if (t >= 1) { const bool hit = oddrow && ((lane & 15) == ((t - 1) & 15)); if (t <= 16) yk0 = hit ? yprev : yk0; else yk1 = hit ? yprev : yk1; }
;                 }
	v_pk_mul_f32 v[150:151], v[142:143], v[126:127]
	v_pk_fma_f32 v[150:151], v[144:145], v[134:135], v[150:151]
	v_pk_mul_f32 v[152:153], v[142:143], v[232:233]
	v_add_f32_e32 v154, v150, v151
	v_pk_fma_f32 v[152:153], v[144:145], v[234:235], v[152:153]
	v_pk_mul_f32 v[146:147], v[142:143], v[128:129]
	v_add_f32_dpp v154, v154, v154 quad_perm:[1,0,3,2] row_mask:0xf bank_mask:0xf bound_ctrl:1
	v_pk_mul_f32 v[148:149], v[144:145], v[136:137]
	v_add_f32_e32 v163, v152, v153
	v_add_f32_dpp v154, v154, v154 quad_perm:[2,3,0,1] row_mask:0xf bank_mask:0xf bound_ctrl:1
	v_pk_fma_f32 v[146:147], v[242:243], v[132:133], v[146:147] op_sel:[0,0,0] op_sel_hi:[0,1,1]
	v_pk_fma_f32 v[148:149], v[242:243], v[224:225], v[148:149] op_sel:[0,0,0] op_sel_hi:[0,1,1]
	v_add_f32_dpp v154, v154, v154 row_half_mirror row_mask:0xf bank_mask:0xf bound_ctrl:1
	ds_read_b128 v[206:209], v182 offset:15360
	ds_read_b128 v[210:213], v182 offset:15376
	v_add_f32_dpp v154, v154, v154 row_mirror row_mask:0xf bank_mask:0xf bound_ctrl:1
	ds_read_b64 v[232:233], v182 offset:15392
	ds_read_b128 v[214:217], v183 offset:15360
	v_pk_fma_f32 v[146:147], v[154:155], v[130:131], v[146:147] op_sel_hi:[0,1,1]
	v_pk_fma_f32 v[148:149], v[154:155], v[222:223], v[148:149] op_sel_hi:[0,1,1]
	ds_read_b128 v[218:221], v183 offset:15376
	ds_read_b64 v[234:235], v183 offset:15392
	ds_read_b32 v241, v186 offset:640
	s_waitcnt lgkmcnt(7)
	v_pk_mul_f32 v[150:151], v[146:147], v[190:191]
	v_pk_fma_f32 v[150:151], v[148:149], v[198:199], v[150:151]
	v_pk_mul_f32 v[152:153], v[146:147], v[236:237]
	v_add_f32_e32 v154, v150, v151
	v_pk_fma_f32 v[152:153], v[148:149], v[238:239], v[152:153]
	v_pk_mul_f32 v[142:143], v[146:147], v[192:193]
	v_add_f32_dpp v154, v154, v154 quad_perm:[1,0,3,2] row_mask:0xf bank_mask:0xf bound_ctrl:1
	v_pk_mul_f32 v[144:145], v[148:149], v[200:201]
	v_add_f32_e32 v164, v152, v153
	v_add_f32_dpp v154, v154, v154 quad_perm:[2,3,0,1] row_mask:0xf bank_mask:0xf bound_ctrl:1
	v_pk_fma_f32 v[142:143], v[240:241], v[196:197], v[142:143] op_sel:[0,0,0] op_sel_hi:[0,1,1]
	v_pk_fma_f32 v[144:145], v[240:241], v[204:205], v[144:145] op_sel:[0,0,0] op_sel_hi:[0,1,1]
	v_add_f32_dpp v154, v154, v154 row_half_mirror row_mask:0xf bank_mask:0xf bound_ctrl:1
	ds_read_b128 v[126:129], v182 offset:16896
	ds_read_b128 v[130:133], v182 offset:16912
	v_add_f32_dpp v154, v154, v154 row_mirror row_mask:0xf bank_mask:0xf bound_ctrl:1
	ds_read_b64 v[236:237], v182 offset:16928
	ds_read_b128 v[134:137], v183 offset:16896
	v_pk_fma_f32 v[142:143], v[154:155], v[194:195], v[142:143] op_sel_hi:[0,1,1]
	v_pk_fma_f32 v[144:145], v[154:155], v[202:203], v[144:145] op_sel_hi:[0,1,1]
	ds_read_b128 v[222:225], v183 offset:16912
	ds_read_b64 v[238:239], v183 offset:16928
	ds_read_b32 v242, v186 offset:704
	s_waitcnt lgkmcnt(7)
	v_pk_mul_f32 v[150:151], v[142:143], v[206:207]
	v_pk_fma_f32 v[150:151], v[144:145], v[214:215], v[150:151]
	v_pk_mul_f32 v[152:153], v[142:143], v[228:229]
	v_add_f32_e32 v154, v150, v151
	v_pk_fma_f32 v[152:153], v[144:145], v[230:231], v[152:153]
	v_pk_mul_f32 v[146:147], v[142:143], v[208:209]
	v_add_f32_dpp v154, v154, v154 quad_perm:[1,0,3,2] row_mask:0xf bank_mask:0xf bound_ctrl:1
	v_pk_mul_f32 v[148:149], v[144:145], v[216:217]
	v_add_f32_e32 v165, v152, v153
	v_add_f32_dpp v154, v154, v154 quad_perm:[2,3,0,1] row_mask:0xf bank_mask:0xf bound_ctrl:1
	v_pk_fma_f32 v[146:147], v[240:241], v[212:213], v[146:147] op_sel:[1,0,0] op_sel_hi:[1,1,1]
	v_pk_fma_f32 v[148:149], v[240:241], v[220:221], v[148:149] op_sel:[1,0,0] op_sel_hi:[1,1,1]
	v_add_f32_dpp v154, v154, v154 row_half_mirror row_mask:0xf bank_mask:0xf bound_ctrl:1
	ds_read_b128 v[190:193], v182 offset:18432
	ds_read_b128 v[194:197], v182 offset:18448
	v_add_f32_dpp v154, v154, v154 row_mirror row_mask:0xf bank_mask:0xf bound_ctrl:1
	ds_read_b64 v[228:229], v182 offset:18464
	ds_read_b128 v[198:201], v183 offset:18432
	v_pk_fma_f32 v[146:147], v[154:155], v[210:211], v[146:147] op_sel_hi:[0,1,1]
	v_pk_fma_f32 v[148:149], v[154:155], v[218:219], v[148:149] op_sel_hi:[0,1,1]
	ds_read_b128 v[202:205], v183 offset:18448
	ds_read_b64 v[230:231], v183 offset:18464
	ds_read_b32 v240, v186 offset:768
	s_waitcnt lgkmcnt(7)
	v_pk_mul_f32 v[150:151], v[146:147], v[126:127]
	v_pk_fma_f32 v[150:151], v[148:149], v[134:135], v[150:151]
	v_pk_mul_f32 v[152:153], v[146:147], v[232:233]
	v_add_f32_e32 v154, v150, v151
	v_pk_fma_f32 v[152:153], v[148:149], v[234:235], v[152:153]
	v_pk_mul_f32 v[142:143], v[146:147], v[128:129]
	v_add_f32_dpp v154, v154, v154 quad_perm:[1,0,3,2] row_mask:0xf bank_mask:0xf bound_ctrl:1
	v_pk_mul_f32 v[144:145], v[148:149], v[136:137]
	v_add_f32_e32 v166, v152, v153
	v_add_f32_dpp v154, v154, v154 quad_perm:[2,3,0,1] row_mask:0xf bank_mask:0xf bound_ctrl:1
	v_pk_fma_f32 v[142:143], v[242:243], v[132:133], v[142:143] op_sel:[0,0,0] op_sel_hi:[0,1,1]
	v_pk_fma_f32 v[144:145], v[242:243], v[224:225], v[144:145] op_sel:[0,0,0] op_sel_hi:[0,1,1]
	v_add_f32_dpp v154, v154, v154 row_half_mirror row_mask:0xf bank_mask:0xf bound_ctrl:1
	ds_read_b128 v[206:209], v182 offset:19968
	ds_read_b128 v[210:213], v182 offset:19984
	v_add_f32_dpp v154, v154, v154 row_mirror row_mask:0xf bank_mask:0xf bound_ctrl:1
	ds_read_b64 v[232:233], v182 offset:20000
	ds_read_b128 v[214:217], v183 offset:19968
	v_pk_fma_f32 v[142:143], v[154:155], v[130:131], v[142:143] op_sel_hi:[0,1,1]
	v_pk_fma_f32 v[144:145], v[154:155], v[222:223], v[144:145] op_sel_hi:[0,1,1]
	ds_read_b128 v[218:221], v183 offset:19984
	ds_read_b64 v[234:235], v183 offset:20000
	ds_read_b32 v241, v186 offset:832
	s_waitcnt lgkmcnt(7)
; __device__ __forceinline__ void wkv_phase(const WkvT& W, unsigned char* lds) {
;     ...
;                 for (int t = 0; t < 32; ++t) {
;                     const f32x2 a2 = {nA[0], nA[1]}, w2 = {nA[2], nA[3]}, b2 = {nB[0], nB[1]}, k2 = {nB[2], nB[3]}, r2 = nr; const float v = nv;
;                     if (t + 1 < 32) { nA = *(const f32x4*)(pp + (t + 1) * 384); nB = *(const f32x4*)(pp + (t + 1) * 384 + 4); nr = *(const f32x2*)(pp + (t + 1) * 384 + 8); nv = pv[(t + 1) * 16]; }
;                     float S0 = S.x, S1 = S.y;
;                     float d = S0 * a2.x; d = __builtin_fmaf(S1, a2.y, d);
;                     float t0 = S0 * w2.x; t0 = __builtin_fmaf(v, k2.x, t0); asm volatile("" : "+v"(t0));
;                     float t1 = S1 * w2.y; t1 = __builtin_fmaf(v, k2.y, t1); asm volatile("" : "+v"(t1));
;                     float yprev; const float sa = wkv_reduce(d, ep, yprev);
;                     S0 = __builtin_fmaf(sa, b2.x, t0); asm volatile("" : "+v"(S0));
;                     S1 = __builtin_fmaf(sa, b2.y, t1); asm volatile("" : "+v"(S1));
;                     ep = S0 * r2.x; ep = __builtin_fmaf(S1, r2.y, ep);
;                     S.x = S0; S.y = S1;
;                     if (t >= 1) { const bool hit = oddrow && ((lane & 15) == ((t - 1) & 15)); if (t <= 16) yk0 = hit ? yprev : yk0; else yk1 = hit ? yprev : yk1; }
;                 }
	v_pk_mul_f32 v[150:151], v[142:143], v[190:191]
	v_pk_fma_f32 v[150:151], v[144:145], v[198:199], v[150:151]
	v_pk_mul_f32 v[152:153], v[142:143], v[236:237]
	v_add_f32_e32 v154, v150, v151
	v_pk_fma_f32 v[152:153], v[144:145], v[238:239], v[152:153]
	v_pk_mul_f32 v[146:147], v[142:143], v[192:193]
	v_add_f32_dpp v154, v154, v154 quad_perm:[1,0,3,2] row_mask:0xf bank_mask:0xf bound_ctrl:1
	v_pk_mul_f32 v[148:149], v[144:145], v[200:201]
	v_add_f32_e32 v167, v152, v153
	v_add_f32_dpp v154, v154, v154 quad_perm:[2,3,0,1] row_mask:0xf bank_mask:0xf bound_ctrl:1
	v_pk_fma_f32 v[146:147], v[240:241], v[196:197], v[146:147] op_sel:[0,0,0] op_sel_hi:[0,1,1]
	v_pk_fma_f32 v[148:149], v[240:241], v[204:205], v[148:149] op_sel:[0,0,0] op_sel_hi:[0,1,1]
	v_add_f32_dpp v154, v154, v154 row_half_mirror row_mask:0xf bank_mask:0xf bound_ctrl:1
	ds_read_b128 v[126:129], v182 offset:21504
	ds_read_b128 v[130:133], v182 offset:21520
	v_add_f32_dpp v154, v154, v154 row_mirror row_mask:0xf bank_mask:0xf bound_ctrl:1
	ds_read_b64 v[236:237], v182 offset:21536
	ds_read_b128 v[134:137], v183 offset:21504
	v_pk_fma_f32 v[146:147], v[154:155], v[194:195], v[146:147] op_sel_hi:[0,1,1]
	v_pk_fma_f32 v[148:149], v[154:155], v[202:203], v[148:149] op_sel_hi:[0,1,1]
	ds_read_b128 v[222:225], v183 offset:21520
	ds_read_b64 v[238:239], v183 offset:21536
	ds_read_b32 v242, v186 offset:896
	s_waitcnt lgkmcnt(7)
	v_pk_mul_f32 v[150:151], v[146:147], v[206:207]
	v_pk_fma_f32 v[150:151], v[148:149], v[214:215], v[150:151]
	v_pk_mul_f32 v[152:153], v[146:147], v[228:229]
	v_add_f32_e32 v154, v150, v151
	v_pk_fma_f32 v[152:153], v[148:149], v[230:231], v[152:153]
	v_pk_mul_f32 v[142:143], v[146:147], v[208:209]
	v_add_f32_dpp v154, v154, v154 quad_perm:[1,0,3,2] row_mask:0xf bank_mask:0xf bound_ctrl:1
	v_pk_mul_f32 v[144:145], v[148:149], v[216:217]
	v_add_f32_e32 v168, v152, v153
	v_add_f32_dpp v154, v154, v154 quad_perm:[2,3,0,1] row_mask:0xf bank_mask:0xf bound_ctrl:1
	v_pk_fma_f32 v[142:143], v[240:241], v[212:213], v[142:143] op_sel:[1,0,0] op_sel_hi:[1,1,1]
	v_pk_fma_f32 v[144:145], v[240:241], v[220:221], v[144:145] op_sel:[1,0,0] op_sel_hi:[1,1,1]
	v_add_f32_dpp v154, v154, v154 row_half_mirror row_mask:0xf bank_mask:0xf bound_ctrl:1
	ds_read_b128 v[190:193], v182 offset:23040
	ds_read_b128 v[194:197], v182 offset:23056
	v_add_f32_dpp v154, v154, v154 row_mirror row_mask:0xf bank_mask:0xf bound_ctrl:1
	ds_read_b64 v[228:229], v182 offset:23072
	ds_read_b128 v[198:201], v183 offset:23040
	v_pk_fma_f32 v[142:143], v[154:155], v[210:211], v[142:143] op_sel_hi:[0,1,1]
	v_pk_fma_f32 v[144:145], v[154:155], v[218:219], v[144:145] op_sel_hi:[0,1,1]
	ds_read_b128 v[202:205], v183 offset:23056
	ds_read_b64 v[230:231], v183 offset:23072
	ds_read_b32 v240, v186 offset:960
	s_waitcnt lgkmcnt(7)
	v_pk_mul_f32 v[150:151], v[142:143], v[126:127]
	v_pk_fma_f32 v[150:151], v[144:145], v[134:135], v[150:151]
	v_pk_mul_f32 v[152:153], v[142:143], v[232:233]
	v_add_f32_e32 v154, v150, v151
	v_pk_fma_f32 v[152:153], v[144:145], v[234:235], v[152:153]
	v_pk_mul_f32 v[146:147], v[142:143], v[128:129]
	v_add_f32_dpp v154, v154, v154 quad_perm:[1,0,3,2] row_mask:0xf bank_mask:0xf bound_ctrl:1
	v_pk_mul_f32 v[148:149], v[144:145], v[136:137]
	v_add_f32_e32 v169, v152, v153
	v_add_f32_dpp v154, v154, v154 quad_perm:[2,3,0,1] row_mask:0xf bank_mask:0xf bound_ctrl:1
	v_pk_fma_f32 v[146:147], v[242:243], v[132:133], v[146:147] op_sel:[0,0,0] op_sel_hi:[0,1,1]
	v_pk_fma_f32 v[148:149], v[242:243], v[224:225], v[148:149] op_sel:[0,0,0] op_sel_hi:[0,1,1]
	v_add_f32_dpp v154, v154, v154 row_half_mirror row_mask:0xf bank_mask:0xf bound_ctrl:1
	ds_read_b128 v[206:209], v182 offset:24576
	ds_read_b128 v[210:213], v182 offset:24592
	v_add_f32_dpp v154, v154, v154 row_mirror row_mask:0xf bank_mask:0xf bound_ctrl:1
	ds_read_b64 v[232:233], v182 offset:24608
	ds_read_b128 v[214:217], v183 offset:24576
	v_pk_fma_f32 v[146:147], v[154:155], v[130:131], v[146:147] op_sel_hi:[0,1,1]
	v_pk_fma_f32 v[148:149], v[154:155], v[222:223], v[148:149] op_sel_hi:[0,1,1]
	ds_read_b128 v[218:221], v183 offset:24592
	ds_read_b64 v[234:235], v183 offset:24608
	ds_read_b32 v241, v186 offset:1024
	s_waitcnt lgkmcnt(7)
	v_pk_mul_f32 v[150:151], v[146:147], v[190:191]
	v_pk_fma_f32 v[150:151], v[148:149], v[198:199], v[150:151]
	v_pk_mul_f32 v[152:153], v[146:147], v[236:237]
	v_add_f32_e32 v154, v150, v151
	v_pk_fma_f32 v[152:153], v[148:149], v[238:239], v[152:153]
	v_pk_mul_f32 v[142:143], v[146:147], v[192:193]
	v_add_f32_dpp v154, v154, v154 quad_perm:[1,0,3,2] row_mask:0xf bank_mask:0xf bound_ctrl:1
	v_pk_mul_f32 v[144:145], v[148:149], v[200:201]
	v_add_f32_e32 v170, v152, v153
	v_add_f32_dpp v154, v154, v154 quad_perm:[2,3,0,1] row_mask:0xf bank_mask:0xf bound_ctrl:1
	v_pk_fma_f32 v[142:143], v[240:241], v[196:197], v[142:143] op_sel:[0,0,0] op_sel_hi:[0,1,1]
	v_pk_fma_f32 v[144:145], v[240:241], v[204:205], v[144:145] op_sel:[0,0,0] op_sel_hi:[0,1,1]
	v_add_f32_dpp v154, v154, v154 row_half_mirror row_mask:0xf bank_mask:0xf bound_ctrl:1
	ds_read_b128 v[126:129], v182 offset:26112
	ds_read_b128 v[130:133], v182 offset:26128
	v_add_f32_dpp v154, v154, v154 row_mirror row_mask:0xf bank_mask:0xf bound_ctrl:1
	ds_read_b64 v[236:237], v182 offset:26144
	ds_read_b128 v[134:137], v183 offset:26112
	v_pk_fma_f32 v[142:143], v[154:155], v[194:195], v[142:143] op_sel_hi:[0,1,1]
	v_pk_fma_f32 v[144:145], v[154:155], v[202:203], v[144:145] op_sel_hi:[0,1,1]
	ds_read_b128 v[222:225], v183 offset:26128
	ds_read_b64 v[238:239], v183 offset:26144
	ds_read_b32 v242, v186 offset:1088
	s_waitcnt lgkmcnt(7)
; __device__ __forceinline__ void wkv_phase(const WkvT& W, unsigned char* lds) {
;     ...
;                 for (int t = 0; t < 32; ++t) {
;                     const f32x2 a2 = {nA[0], nA[1]}, w2 = {nA[2], nA[3]}, b2 = {nB[0], nB[1]}, k2 = {nB[2], nB[3]}, r2 = nr; const float v = nv;
;                     if (t + 1 < 32) { nA = *(const f32x4*)(pp + (t + 1) * 384); nB = *(const f32x4*)(pp + (t + 1) * 384 + 4); nr = *(const f32x2*)(pp + (t + 1) * 384 + 8); nv = pv[(t + 1) * 16]; }
;                     float S0 = S.x, S1 = S.y;
;                     float d = S0 * a2.x; d = __builtin_fmaf(S1, a2.y, d);
;                     float t0 = S0 * w2.x; t0 = __builtin_fmaf(v, k2.x, t0); asm volatile("" : "+v"(t0));
;                     float t1 = S1 * w2.y; t1 = __builtin_fmaf(v, k2.y, t1); asm volatile("" : "+v"(t1));
;                     float yprev; const float sa = wkv_reduce(d, ep, yprev);
;                     S0 = __builtin_fmaf(sa, b2.x, t0); asm volatile("" : "+v"(S0));
;                     S1 = __builtin_fmaf(sa, b2.y, t1); asm volatile("" : "+v"(S1));
;                     ep = S0 * r2.x; ep = __builtin_fmaf(S1, r2.y, ep);
;                     S.x = S0; S.y = S1;
;                     if (t >= 1) { const bool hit = oddrow && ((lane & 15) == ((t - 1) & 15)); if (t <= 16) yk0 = hit ? yprev : yk0; else yk1 = hit ? yprev : yk1; }
;                 }
;                 { float ylast; (void)wkv_reduce(0.f, ep, ylast); yk1 = (oddrow && (lane & 15) == 15) ? ylast : yk1; }
;                 if (oddrow) { sY[bi * 512 + (lane & 15) * 16 + il] = yk0; sY[bi * 512 + (16 + (lane & 15)) * 16 + il] = yk1; }
	v_pk_mul_f32 v[150:151], v[142:143], v[206:207]
	v_pk_fma_f32 v[150:151], v[144:145], v[214:215], v[150:151]
	v_pk_mul_f32 v[152:153], v[142:143], v[228:229]
	v_add_f32_e32 v154, v150, v151
	v_pk_fma_f32 v[152:153], v[144:145], v[230:231], v[152:153]
	v_pk_mul_f32 v[146:147], v[142:143], v[208:209]
	v_add_f32_dpp v154, v154, v154 quad_perm:[1,0,3,2] row_mask:0xf bank_mask:0xf bound_ctrl:1
	v_pk_mul_f32 v[148:149], v[144:145], v[216:217]
	v_add_f32_e32 v171, v152, v153
	v_add_f32_dpp v154, v154, v154 quad_perm:[2,3,0,1] row_mask:0xf bank_mask:0xf bound_ctrl:1
	v_pk_fma_f32 v[146:147], v[240:241], v[212:213], v[146:147] op_sel:[1,0,0] op_sel_hi:[1,1,1]
	v_pk_fma_f32 v[148:149], v[240:241], v[220:221], v[148:149] op_sel:[1,0,0] op_sel_hi:[1,1,1]
	v_add_f32_dpp v154, v154, v154 row_half_mirror row_mask:0xf bank_mask:0xf bound_ctrl:1
	ds_read_b128 v[190:193], v182 offset:27648
	ds_read_b128 v[194:197], v182 offset:27664
	v_add_f32_dpp v154, v154, v154 row_mirror row_mask:0xf bank_mask:0xf bound_ctrl:1
	ds_read_b64 v[228:229], v182 offset:27680
	ds_read_b128 v[198:201], v183 offset:27648
	v_pk_fma_f32 v[146:147], v[154:155], v[210:211], v[146:147] op_sel_hi:[0,1,1]
	v_pk_fma_f32 v[148:149], v[154:155], v[218:219], v[148:149] op_sel_hi:[0,1,1]
	ds_read_b128 v[202:205], v183 offset:27664
	ds_read_b64 v[230:231], v183 offset:27680
	ds_read_b32 v240, v186 offset:1152
	s_waitcnt lgkmcnt(7)
	v_add_f32_dpp v172, v156, v156 row_ror:8 row_mask:0xf bank_mask:0x3
	v_add_f32_dpp v172, v164, v164 row_ror:8 row_mask:0xf bank_mask:0xc
	v_add_f32_dpp v173, v157, v157 row_ror:8 row_mask:0xf bank_mask:0x3
	v_add_f32_dpp v173, v165, v165 row_ror:8 row_mask:0xf bank_mask:0xc
	v_add_f32_dpp v174, v158, v158 row_ror:8 row_mask:0xf bank_mask:0x3
	v_add_f32_dpp v174, v166, v166 row_ror:8 row_mask:0xf bank_mask:0xc
	v_add_f32_dpp v175, v159, v159 row_ror:8 row_mask:0xf bank_mask:0x3
	v_add_f32_dpp v175, v167, v167 row_ror:8 row_mask:0xf bank_mask:0xc
	v_add_f32_dpp v176, v160, v160 row_ror:8 row_mask:0xf bank_mask:0x3
	v_add_f32_dpp v176, v168, v168 row_ror:8 row_mask:0xf bank_mask:0xc
	v_add_f32_dpp v177, v161, v161 row_ror:8 row_mask:0xf bank_mask:0x3
	v_add_f32_dpp v177, v169, v169 row_ror:8 row_mask:0xf bank_mask:0xc
	v_add_f32_dpp v178, v162, v162 row_ror:8 row_mask:0xf bank_mask:0x3
	v_add_f32_dpp v178, v170, v170 row_ror:8 row_mask:0xf bank_mask:0xc
	v_add_f32_dpp v179, v163, v163 row_ror:8 row_mask:0xf bank_mask:0x3
	v_add_f32_dpp v179, v171, v171 row_ror:8 row_mask:0xf bank_mask:0xc
	v_add_f32_dpp v156, v172, v172 row_half_mirror row_mask:0xf bank_mask:0x5
	v_add_f32_dpp v156, v176, v176 row_half_mirror row_mask:0xf bank_mask:0xa
	v_add_f32_dpp v157, v173, v173 row_half_mirror row_mask:0xf bank_mask:0x5
	v_add_f32_dpp v157, v177, v177 row_half_mirror row_mask:0xf bank_mask:0xa
	v_add_f32_dpp v158, v174, v174 row_half_mirror row_mask:0xf bank_mask:0x5
	v_add_f32_dpp v158, v178, v178 row_half_mirror row_mask:0xf bank_mask:0xa
	v_add_f32_dpp v159, v175, v175 row_half_mirror row_mask:0xf bank_mask:0x5
	v_add_f32_dpp v159, v179, v179 row_half_mirror row_mask:0xf bank_mask:0xa
	v_cndmask_b32_e64 v176, v158, v156, s[14:15]
	v_cndmask_b32_e64 v177, v159, v157, s[14:15]
	v_cndmask_b32_e64 v178, v156, v158, s[14:15]
	v_cndmask_b32_e64 v179, v157, v159, s[14:15]
	v_add_f32_dpp v172, v176, v178 quad_perm:[2,3,0,1] row_mask:0xf bank_mask:0xf
	v_add_f32_dpp v173, v177, v179 quad_perm:[2,3,0,1] row_mask:0xf bank_mask:0xf
	v_cndmask_b32_e64 v176, v173, v172, s[16:17]
	v_cndmask_b32_e64 v178, v172, v173, s[16:17]
	s_nop 0
	v_add_f32_dpp v180, v176, v178 quad_perm:[1,0,3,2] row_mask:0xf bank_mask:0xf
	v_pk_mul_f32 v[150:151], v[146:147], v[126:127]
	v_pk_fma_f32 v[150:151], v[148:149], v[134:135], v[150:151]
	v_pk_mul_f32 v[152:153], v[146:147], v[232:233]
	v_add_f32_e32 v154, v150, v151
	v_pk_fma_f32 v[152:153], v[148:149], v[234:235], v[152:153]
	v_pk_mul_f32 v[142:143], v[146:147], v[128:129]
	v_add_f32_dpp v154, v154, v154 quad_perm:[1,0,3,2] row_mask:0xf bank_mask:0xf bound_ctrl:1
	v_pk_mul_f32 v[144:145], v[148:149], v[136:137]
	v_add_f32_e32 v156, v152, v153
	v_add_f32_dpp v154, v154, v154 quad_perm:[2,3,0,1] row_mask:0xf bank_mask:0xf bound_ctrl:1
	v_pk_fma_f32 v[142:143], v[242:243], v[132:133], v[142:143] op_sel:[0,0,0] op_sel_hi:[0,1,1]
	v_pk_fma_f32 v[144:145], v[242:243], v[224:225], v[144:145] op_sel:[0,0,0] op_sel_hi:[0,1,1]
	v_add_f32_dpp v154, v154, v154 row_half_mirror row_mask:0xf bank_mask:0xf bound_ctrl:1
	ds_read_b128 v[206:209], v182 offset:29184
	ds_read_b128 v[210:213], v182 offset:29200
	v_add_f32_dpp v154, v154, v154 row_mirror row_mask:0xf bank_mask:0xf bound_ctrl:1
	ds_read_b64 v[232:233], v182 offset:29216
	ds_read_b128 v[214:217], v183 offset:29184
	v_pk_fma_f32 v[142:143], v[154:155], v[130:131], v[142:143] op_sel_hi:[0,1,1]
	v_pk_fma_f32 v[144:145], v[154:155], v[222:223], v[144:145] op_sel_hi:[0,1,1]
	ds_read_b128 v[218:221], v183 offset:29200
	ds_read_b64 v[234:235], v183 offset:29216
	ds_read_b32 v241, v186 offset:1216
	s_waitcnt lgkmcnt(7)
; __device__ __forceinline__ void wkv_phase(const WkvT& W, unsigned char* lds) {
;     ...
;                 for (int t = 0; t < 32; ++t) {
;                     const f32x2 a2 = {nA[0], nA[1]}, w2 = {nA[2], nA[3]}, b2 = {nB[0], nB[1]}, k2 = {nB[2], nB[3]}, r2 = nr; const float v = nv;
;                     if (t + 1 < 32) { nA = *(const f32x4*)(pp + (t + 1) * 384); nB = *(const f32x4*)(pp + (t + 1) * 384 + 4); nr = *(const f32x2*)(pp + (t + 1) * 384 + 8); nv = pv[(t + 1) * 16]; }
;                     float S0 = S.x, S1 = S.y;
;                     float d = S0 * a2.x; d = __builtin_fmaf(S1, a2.y, d);
;                     float t0 = S0 * w2.x; t0 = __builtin_fmaf(v, k2.x, t0); asm volatile("" : "+v"(t0));
;                     float t1 = S1 * w2.y; t1 = __builtin_fmaf(v, k2.y, t1); asm volatile("" : "+v"(t1));
;                     float yprev; const float sa = wkv_reduce(d, ep, yprev);
;                     S0 = __builtin_fmaf(sa, b2.x, t0); asm volatile("" : "+v"(S0));
;                     S1 = __builtin_fmaf(sa, b2.y, t1); asm volatile("" : "+v"(S1));
;                     ep = S0 * r2.x; ep = __builtin_fmaf(S1, r2.y, ep);
;                     S.x = S0; S.y = S1;
;                     if (t >= 1) { const bool hit = oddrow && ((lane & 15) == ((t - 1) & 15)); if (t <= 16) yk0 = hit ? yprev : yk0; else yk1 = hit ? yprev : yk1; }
;                 }
	v_pk_mul_f32 v[150:151], v[142:143], v[190:191]
	v_pk_fma_f32 v[150:151], v[144:145], v[198:199], v[150:151]
	v_pk_mul_f32 v[152:153], v[142:143], v[236:237]
	v_add_f32_e32 v154, v150, v151
	v_pk_fma_f32 v[152:153], v[144:145], v[238:239], v[152:153]
	v_pk_mul_f32 v[146:147], v[142:143], v[192:193]
	v_add_f32_dpp v154, v154, v154 quad_perm:[1,0,3,2] row_mask:0xf bank_mask:0xf bound_ctrl:1
	v_pk_mul_f32 v[148:149], v[144:145], v[200:201]
	v_add_f32_e32 v157, v152, v153
	v_add_f32_dpp v154, v154, v154 quad_perm:[2,3,0,1] row_mask:0xf bank_mask:0xf bound_ctrl:1
	v_pk_fma_f32 v[146:147], v[240:241], v[196:197], v[146:147] op_sel:[0,0,0] op_sel_hi:[0,1,1]
	v_pk_fma_f32 v[148:149], v[240:241], v[204:205], v[148:149] op_sel:[0,0,0] op_sel_hi:[0,1,1]
	v_add_f32_dpp v154, v154, v154 row_half_mirror row_mask:0xf bank_mask:0xf bound_ctrl:1
	ds_read_b128 v[126:129], v182 offset:30720
	ds_read_b128 v[130:133], v182 offset:30736
	v_add_f32_dpp v154, v154, v154 row_mirror row_mask:0xf bank_mask:0xf bound_ctrl:1
	ds_read_b64 v[236:237], v182 offset:30752
	ds_read_b128 v[134:137], v183 offset:30720
	v_pk_fma_f32 v[146:147], v[154:155], v[194:195], v[146:147] op_sel_hi:[0,1,1]
	v_pk_fma_f32 v[148:149], v[154:155], v[202:203], v[148:149] op_sel_hi:[0,1,1]
	ds_read_b128 v[222:225], v183 offset:30736
	ds_read_b64 v[238:239], v183 offset:30752
	ds_read_b32 v242, v186 offset:1280
	s_waitcnt lgkmcnt(7)
	v_pk_mul_f32 v[150:151], v[146:147], v[206:207]
	v_pk_fma_f32 v[150:151], v[148:149], v[214:215], v[150:151]
	v_pk_mul_f32 v[152:153], v[146:147], v[228:229]
	v_add_f32_e32 v154, v150, v151
	v_pk_fma_f32 v[152:153], v[148:149], v[230:231], v[152:153]
	v_pk_mul_f32 v[142:143], v[146:147], v[208:209]
	v_add_f32_dpp v154, v154, v154 quad_perm:[1,0,3,2] row_mask:0xf bank_mask:0xf bound_ctrl:1
	v_pk_mul_f32 v[144:145], v[148:149], v[216:217]
	v_add_f32_e32 v158, v152, v153
	v_add_f32_dpp v154, v154, v154 quad_perm:[2,3,0,1] row_mask:0xf bank_mask:0xf bound_ctrl:1
	v_pk_fma_f32 v[142:143], v[240:241], v[212:213], v[142:143] op_sel:[1,0,0] op_sel_hi:[1,1,1]
	v_pk_fma_f32 v[144:145], v[240:241], v[220:221], v[144:145] op_sel:[1,0,0] op_sel_hi:[1,1,1]
	v_add_f32_dpp v154, v154, v154 row_half_mirror row_mask:0xf bank_mask:0xf bound_ctrl:1
	ds_read_b128 v[190:193], v182 offset:32256
	ds_read_b128 v[194:197], v182 offset:32272
	v_add_f32_dpp v154, v154, v154 row_mirror row_mask:0xf bank_mask:0xf bound_ctrl:1
	ds_read_b64 v[228:229], v182 offset:32288
	ds_read_b128 v[198:201], v183 offset:32256
	v_pk_fma_f32 v[142:143], v[154:155], v[210:211], v[142:143] op_sel_hi:[0,1,1]
	v_pk_fma_f32 v[144:145], v[154:155], v[218:219], v[144:145] op_sel_hi:[0,1,1]
	ds_read_b128 v[202:205], v183 offset:32272
	ds_read_b64 v[230:231], v183 offset:32288
	ds_read_b32 v240, v186 offset:1344
	s_waitcnt lgkmcnt(7)
	v_pk_mul_f32 v[150:151], v[142:143], v[126:127]
	v_pk_fma_f32 v[150:151], v[144:145], v[134:135], v[150:151]
	v_pk_mul_f32 v[152:153], v[142:143], v[232:233]
	v_add_f32_e32 v154, v150, v151
	v_pk_fma_f32 v[152:153], v[144:145], v[234:235], v[152:153]
	v_pk_mul_f32 v[146:147], v[142:143], v[128:129]
	v_add_f32_dpp v154, v154, v154 quad_perm:[1,0,3,2] row_mask:0xf bank_mask:0xf bound_ctrl:1
	v_pk_mul_f32 v[148:149], v[144:145], v[136:137]
	v_add_f32_e32 v159, v152, v153
	v_add_f32_dpp v154, v154, v154 quad_perm:[2,3,0,1] row_mask:0xf bank_mask:0xf bound_ctrl:1
	v_pk_fma_f32 v[146:147], v[242:243], v[132:133], v[146:147] op_sel:[0,0,0] op_sel_hi:[0,1,1]
	v_pk_fma_f32 v[148:149], v[242:243], v[224:225], v[148:149] op_sel:[0,0,0] op_sel_hi:[0,1,1]
	v_add_f32_dpp v154, v154, v154 row_half_mirror row_mask:0xf bank_mask:0xf bound_ctrl:1
	ds_read_b128 v[206:209], v182 offset:33792
	ds_read_b128 v[210:213], v182 offset:33808
	v_add_f32_dpp v154, v154, v154 row_mirror row_mask:0xf bank_mask:0xf bound_ctrl:1
	ds_read_b64 v[232:233], v182 offset:33824
	ds_read_b128 v[214:217], v183 offset:33792
	v_pk_fma_f32 v[146:147], v[154:155], v[130:131], v[146:147] op_sel_hi:[0,1,1]
	v_pk_fma_f32 v[148:149], v[154:155], v[222:223], v[148:149] op_sel_hi:[0,1,1]
	ds_read_b128 v[218:221], v183 offset:33808
	ds_read_b64 v[234:235], v183 offset:33824
	ds_read_b32 v241, v186 offset:1408
	s_waitcnt lgkmcnt(7)
	v_pk_mul_f32 v[150:151], v[146:147], v[190:191]
	v_pk_fma_f32 v[150:151], v[148:149], v[198:199], v[150:151]
	v_pk_mul_f32 v[152:153], v[146:147], v[236:237]
	v_add_f32_e32 v154, v150, v151
	v_pk_fma_f32 v[152:153], v[148:149], v[238:239], v[152:153]
	v_pk_mul_f32 v[142:143], v[146:147], v[192:193]
	v_add_f32_dpp v154, v154, v154 quad_perm:[1,0,3,2] row_mask:0xf bank_mask:0xf bound_ctrl:1
	v_pk_mul_f32 v[144:145], v[148:149], v[200:201]
	v_add_f32_e32 v160, v152, v153
	v_add_f32_dpp v154, v154, v154 quad_perm:[2,3,0,1] row_mask:0xf bank_mask:0xf bound_ctrl:1
	v_pk_fma_f32 v[142:143], v[240:241], v[196:197], v[142:143] op_sel:[0,0,0] op_sel_hi:[0,1,1]
	v_pk_fma_f32 v[144:145], v[240:241], v[204:205], v[144:145] op_sel:[0,0,0] op_sel_hi:[0,1,1]
	v_add_f32_dpp v154, v154, v154 row_half_mirror row_mask:0xf bank_mask:0xf bound_ctrl:1
	ds_read_b128 v[126:129], v182 offset:35328
	ds_read_b128 v[130:133], v182 offset:35344
	v_add_f32_dpp v154, v154, v154 row_mirror row_mask:0xf bank_mask:0xf bound_ctrl:1
	ds_read_b64 v[236:237], v182 offset:35360
	ds_read_b128 v[134:137], v183 offset:35328
	v_pk_fma_f32 v[142:143], v[154:155], v[194:195], v[142:143] op_sel_hi:[0,1,1]
	v_pk_fma_f32 v[144:145], v[154:155], v[202:203], v[144:145] op_sel_hi:[0,1,1]
	ds_read_b128 v[222:225], v183 offset:35344
	ds_read_b64 v[238:239], v183 offset:35360
	ds_read_b32 v242, v186 offset:1472
	s_waitcnt lgkmcnt(7)
; __device__ __forceinline__ void wkv_phase(const WkvT& W, unsigned char* lds) {
;     ...
;                 const float* pp = sP + bo + jj * 12;
;                 const float* pv = sV + bi * 512 + il;
;                 f32x4 nA = *(const f32x4*)pp, nB = *(const f32x4*)(pp + 4); f32x2 nr = *(const f32x2*)(pp + 8); float nv = pv[0];
;                 float yk0 = 0.f, yk1 = 0.f, ep = 0.f;
;                 const bool oddrow = (lane & 16) != 0;
; #pragma unroll
;                 for (int t = 0; t < 32; ++t) {
;                     const f32x2 a2 = {nA[0], nA[1]}, w2 = {nA[2], nA[3]}, b2 = {nB[0], nB[1]}, k2 = {nB[2], nB[3]}, r2 = nr; const float v = nv;
;                     if (t + 1 < 32) { nA = *(const f32x4*)(pp + (t + 1) * 384); nB = *(const f32x4*)(pp + (t + 1) * 384 + 4); nr = *(const f32x2*)(pp + (t + 1) * 384 + 8); nv = pv[(t + 1) * 16]; }
;                     float S0 = S.x, S1 = S.y;
;                     float d = S0 * a2.x; d = __builtin_fmaf(S1, a2.y, d);
;                     float t0 = S0 * w2.x; t0 = __builtin_fmaf(v, k2.x, t0); asm volatile("" : "+v"(t0));
;                     float t1 = S1 * w2.y; t1 = __builtin_fmaf(v, k2.y, t1); asm volatile("" : "+v"(t1));
;                     float yprev; const float sa = wkv_reduce(d, ep, yprev);
;                     S0 = __builtin_fmaf(sa, b2.x, t0); asm volatile("" : "+v"(S0));
;                     S1 = __builtin_fmaf(sa, b2.y, t1); asm volatile("" : "+v"(S1));
;                     ep = S0 * r2.x; ep = __builtin_fmaf(S1, r2.y, ep);
;                     S.x = S0; S.y = S1;
;                     if (t >= 1) { const bool hit = oddrow && ((lane & 15) == ((t - 1) & 15)); if (t <= 16) yk0 = hit ? yprev : yk0; else yk1 = hit ? yprev : yk1; }
;                 }
	v_pk_mul_f32 v[150:151], v[142:143], v[206:207]
	v_pk_fma_f32 v[150:151], v[144:145], v[214:215], v[150:151]
	v_pk_mul_f32 v[152:153], v[142:143], v[228:229]
	v_add_f32_e32 v154, v150, v151
	v_pk_fma_f32 v[152:153], v[144:145], v[230:231], v[152:153]
	v_pk_mul_f32 v[146:147], v[142:143], v[208:209]
	v_add_f32_dpp v154, v154, v154 quad_perm:[1,0,3,2] row_mask:0xf bank_mask:0xf bound_ctrl:1
	v_pk_mul_f32 v[148:149], v[144:145], v[216:217]
	v_add_f32_e32 v161, v152, v153
	v_add_f32_dpp v154, v154, v154 quad_perm:[2,3,0,1] row_mask:0xf bank_mask:0xf bound_ctrl:1
	v_pk_fma_f32 v[146:147], v[240:241], v[212:213], v[146:147] op_sel:[1,0,0] op_sel_hi:[1,1,1]
	v_pk_fma_f32 v[148:149], v[240:241], v[220:221], v[148:149] op_sel:[1,0,0] op_sel_hi:[1,1,1]
	v_add_f32_dpp v154, v154, v154 row_half_mirror row_mask:0xf bank_mask:0xf bound_ctrl:1
	ds_read_b128 v[190:193], v182 offset:36864
	ds_read_b128 v[194:197], v182 offset:36880
	v_add_f32_dpp v154, v154, v154 row_mirror row_mask:0xf bank_mask:0xf bound_ctrl:1
	ds_read_b64 v[228:229], v182 offset:36896
	ds_read_b128 v[198:201], v183 offset:36864
	v_pk_fma_f32 v[146:147], v[154:155], v[210:211], v[146:147] op_sel_hi:[0,1,1]
	v_pk_fma_f32 v[148:149], v[154:155], v[218:219], v[148:149] op_sel_hi:[0,1,1]
	ds_read_b128 v[202:205], v183 offset:36880
	ds_read_b64 v[230:231], v183 offset:36896
	ds_read_b32 v240, v186 offset:1536
	s_waitcnt lgkmcnt(7)
	v_pk_mul_f32 v[150:151], v[146:147], v[126:127]
	v_pk_fma_f32 v[150:151], v[148:149], v[134:135], v[150:151]
	v_pk_mul_f32 v[152:153], v[146:147], v[232:233]
	v_add_f32_e32 v154, v150, v151
	v_pk_fma_f32 v[152:153], v[148:149], v[234:235], v[152:153]
	v_pk_mul_f32 v[142:143], v[146:147], v[128:129]
	v_add_f32_dpp v154, v154, v154 quad_perm:[1,0,3,2] row_mask:0xf bank_mask:0xf bound_ctrl:1
	v_pk_mul_f32 v[144:145], v[148:149], v[136:137]
	v_add_f32_e32 v162, v152, v153
	v_add_f32_dpp v154, v154, v154 quad_perm:[2,3,0,1] row_mask:0xf bank_mask:0xf bound_ctrl:1
	v_pk_fma_f32 v[142:143], v[242:243], v[132:133], v[142:143] op_sel:[0,0,0] op_sel_hi:[0,1,1]
	v_pk_fma_f32 v[144:145], v[242:243], v[224:225], v[144:145] op_sel:[0,0,0] op_sel_hi:[0,1,1]
	v_add_f32_dpp v154, v154, v154 row_half_mirror row_mask:0xf bank_mask:0xf bound_ctrl:1
	ds_read_b128 v[206:209], v182 offset:38400
	ds_read_b128 v[210:213], v182 offset:38416
	v_add_f32_dpp v154, v154, v154 row_mirror row_mask:0xf bank_mask:0xf bound_ctrl:1
	ds_read_b64 v[232:233], v182 offset:38432
	ds_read_b128 v[214:217], v183 offset:38400
	v_pk_fma_f32 v[142:143], v[154:155], v[130:131], v[142:143] op_sel_hi:[0,1,1]
	v_pk_fma_f32 v[144:145], v[154:155], v[222:223], v[144:145] op_sel_hi:[0,1,1]
	ds_read_b128 v[218:221], v183 offset:38416
	ds_read_b64 v[234:235], v183 offset:38432
	ds_read_b32 v241, v186 offset:1600
	s_waitcnt lgkmcnt(7)
	v_pk_mul_f32 v[150:151], v[142:143], v[190:191]
	v_pk_fma_f32 v[150:151], v[144:145], v[198:199], v[150:151]
	v_pk_mul_f32 v[152:153], v[142:143], v[236:237]
	v_add_f32_e32 v154, v150, v151
	v_pk_fma_f32 v[152:153], v[144:145], v[238:239], v[152:153]
	v_pk_mul_f32 v[146:147], v[142:143], v[192:193]
	v_add_f32_dpp v154, v154, v154 quad_perm:[1,0,3,2] row_mask:0xf bank_mask:0xf bound_ctrl:1
	v_pk_mul_f32 v[148:149], v[144:145], v[200:201]
	v_add_f32_e32 v163, v152, v153
	v_add_f32_dpp v154, v154, v154 quad_perm:[2,3,0,1] row_mask:0xf bank_mask:0xf bound_ctrl:1
	v_pk_fma_f32 v[146:147], v[240:241], v[196:197], v[146:147] op_sel:[0,0,0] op_sel_hi:[0,1,1]
	v_pk_fma_f32 v[148:149], v[240:241], v[204:205], v[148:149] op_sel:[0,0,0] op_sel_hi:[0,1,1]
	v_add_f32_dpp v154, v154, v154 row_half_mirror row_mask:0xf bank_mask:0xf bound_ctrl:1
	ds_read_b128 v[126:129], v182 offset:39936
	ds_read_b128 v[130:133], v182 offset:39952
	v_add_f32_dpp v154, v154, v154 row_mirror row_mask:0xf bank_mask:0xf bound_ctrl:1
	ds_read_b64 v[236:237], v182 offset:39968
	ds_read_b128 v[134:137], v183 offset:39936
	v_pk_fma_f32 v[146:147], v[154:155], v[194:195], v[146:147] op_sel_hi:[0,1,1]
	v_pk_fma_f32 v[148:149], v[154:155], v[202:203], v[148:149] op_sel_hi:[0,1,1]
	ds_read_b128 v[222:225], v183 offset:39952
	ds_read_b64 v[238:239], v183 offset:39968
	ds_read_b32 v242, v186 offset:1664
	s_waitcnt lgkmcnt(7)
	v_pk_mul_f32 v[150:151], v[146:147], v[206:207]
	v_pk_fma_f32 v[150:151], v[148:149], v[214:215], v[150:151]
	v_pk_mul_f32 v[152:153], v[146:147], v[228:229]
	v_add_f32_e32 v154, v150, v151
	v_pk_fma_f32 v[152:153], v[148:149], v[230:231], v[152:153]
	v_pk_mul_f32 v[142:143], v[146:147], v[208:209]
	v_add_f32_dpp v154, v154, v154 quad_perm:[1,0,3,2] row_mask:0xf bank_mask:0xf bound_ctrl:1
	v_pk_mul_f32 v[144:145], v[148:149], v[216:217]
	v_add_f32_e32 v164, v152, v153
	v_add_f32_dpp v154, v154, v154 quad_perm:[2,3,0,1] row_mask:0xf bank_mask:0xf bound_ctrl:1
	v_pk_fma_f32 v[142:143], v[240:241], v[212:213], v[142:143] op_sel:[1,0,0] op_sel_hi:[1,1,1]
	v_pk_fma_f32 v[144:145], v[240:241], v[220:221], v[144:145] op_sel:[1,0,0] op_sel_hi:[1,1,1]
	v_add_f32_dpp v154, v154, v154 row_half_mirror row_mask:0xf bank_mask:0xf bound_ctrl:1
	ds_read_b128 v[190:193], v182 offset:41472
	ds_read_b128 v[194:197], v182 offset:41488
	v_add_f32_dpp v154, v154, v154 row_mirror row_mask:0xf bank_mask:0xf bound_ctrl:1
	ds_read_b64 v[228:229], v182 offset:41504
	ds_read_b128 v[198:201], v183 offset:41472
	v_pk_fma_f32 v[142:143], v[154:155], v[210:211], v[142:143] op_sel_hi:[0,1,1]
	v_pk_fma_f32 v[144:145], v[154:155], v[218:219], v[144:145] op_sel_hi:[0,1,1]
	ds_read_b128 v[202:205], v183 offset:41488
	ds_read_b64 v[230:231], v183 offset:41504
	ds_read_b32 v240, v186 offset:1728
	s_waitcnt lgkmcnt(7)
; __device__ __forceinline__ void wkv_phase(const WkvT& W, unsigned char* lds) {
;     ...
;                 const float* pp = sP + bo + jj * 12;
;                 const float* pv = sV + bi * 512 + il;
;                 f32x4 nA = *(const f32x4*)pp, nB = *(const f32x4*)(pp + 4); f32x2 nr = *(const f32x2*)(pp + 8); float nv = pv[0];
;                 float yk0 = 0.f, yk1 = 0.f, ep = 0.f;
;                 const bool oddrow = (lane & 16) != 0;
; #pragma unroll
;                 for (int t = 0; t < 32; ++t) {
;                     const f32x2 a2 = {nA[0], nA[1]}, w2 = {nA[2], nA[3]}, b2 = {nB[0], nB[1]}, k2 = {nB[2], nB[3]}, r2 = nr; const float v = nv;
;                     if (t + 1 < 32) { nA = *(const f32x4*)(pp + (t + 1) * 384); nB = *(const f32x4*)(pp + (t + 1) * 384 + 4); nr = *(const f32x2*)(pp + (t + 1) * 384 + 8); nv = pv[(t + 1) * 16]; }
;                     float S0 = S.x, S1 = S.y;
;                     float d = S0 * a2.x; d = __builtin_fmaf(S1, a2.y, d);
;                     float t0 = S0 * w2.x; t0 = __builtin_fmaf(v, k2.x, t0); asm volatile("" : "+v"(t0));
;                     float t1 = S1 * w2.y; t1 = __builtin_fmaf(v, k2.y, t1); asm volatile("" : "+v"(t1));
;                     float yprev; const float sa = wkv_reduce(d, ep, yprev);
;                     S0 = __builtin_fmaf(sa, b2.x, t0); asm volatile("" : "+v"(S0));
;                     S1 = __builtin_fmaf(sa, b2.y, t1); asm volatile("" : "+v"(S1));
;                     ep = S0 * r2.x; ep = __builtin_fmaf(S1, r2.y, ep);
;                     S.x = S0; S.y = S1;
;                     if (t >= 1) { const bool hit = oddrow && ((lane & 15) == ((t - 1) & 15)); if (t <= 16) yk0 = hit ? yprev : yk0; else yk1 = hit ? yprev : yk1; }
;                 }
	v_pk_mul_f32 v[150:151], v[142:143], v[126:127]
	v_pk_fma_f32 v[150:151], v[144:145], v[134:135], v[150:151]
	v_pk_mul_f32 v[152:153], v[142:143], v[232:233]
	v_add_f32_e32 v154, v150, v151
	v_pk_fma_f32 v[152:153], v[144:145], v[234:235], v[152:153]
	v_pk_mul_f32 v[146:147], v[142:143], v[128:129]
	v_add_f32_dpp v154, v154, v154 quad_perm:[1,0,3,2] row_mask:0xf bank_mask:0xf bound_ctrl:1
	v_pk_mul_f32 v[148:149], v[144:145], v[136:137]
	v_add_f32_e32 v165, v152, v153
	v_add_f32_dpp v154, v154, v154 quad_perm:[2,3,0,1] row_mask:0xf bank_mask:0xf bound_ctrl:1
	v_pk_fma_f32 v[146:147], v[242:243], v[132:133], v[146:147] op_sel:[0,0,0] op_sel_hi:[0,1,1]
	v_pk_fma_f32 v[148:149], v[242:243], v[224:225], v[148:149] op_sel:[0,0,0] op_sel_hi:[0,1,1]
	v_add_f32_dpp v154, v154, v154 row_half_mirror row_mask:0xf bank_mask:0xf bound_ctrl:1
	ds_read_b128 v[206:209], v182 offset:43008
	ds_read_b128 v[210:213], v182 offset:43024
	v_add_f32_dpp v154, v154, v154 row_mirror row_mask:0xf bank_mask:0xf bound_ctrl:1
	ds_read_b64 v[232:233], v182 offset:43040
	ds_read_b128 v[214:217], v183 offset:43008
	v_pk_fma_f32 v[146:147], v[154:155], v[130:131], v[146:147] op_sel_hi:[0,1,1]
	v_pk_fma_f32 v[148:149], v[154:155], v[222:223], v[148:149] op_sel_hi:[0,1,1]
	ds_read_b128 v[218:221], v183 offset:43024
	ds_read_b64 v[234:235], v183 offset:43040
	ds_read_b32 v241, v186 offset:1792
	s_waitcnt lgkmcnt(7)
	v_pk_mul_f32 v[150:151], v[146:147], v[190:191]
	v_pk_fma_f32 v[150:151], v[148:149], v[198:199], v[150:151]
	v_pk_mul_f32 v[152:153], v[146:147], v[236:237]
	v_add_f32_e32 v154, v150, v151
	v_pk_fma_f32 v[152:153], v[148:149], v[238:239], v[152:153]
	v_pk_mul_f32 v[142:143], v[146:147], v[192:193]
	v_add_f32_dpp v154, v154, v154 quad_perm:[1,0,3,2] row_mask:0xf bank_mask:0xf bound_ctrl:1
	v_pk_mul_f32 v[144:145], v[148:149], v[200:201]
	v_add_f32_e32 v166, v152, v153
	v_add_f32_dpp v154, v154, v154 quad_perm:[2,3,0,1] row_mask:0xf bank_mask:0xf bound_ctrl:1
	v_pk_fma_f32 v[142:143], v[240:241], v[196:197], v[142:143] op_sel:[0,0,0] op_sel_hi:[0,1,1]
	v_pk_fma_f32 v[144:145], v[240:241], v[204:205], v[144:145] op_sel:[0,0,0] op_sel_hi:[0,1,1]
	v_add_f32_dpp v154, v154, v154 row_half_mirror row_mask:0xf bank_mask:0xf bound_ctrl:1
	ds_read_b128 v[126:129], v182 offset:44544
	ds_read_b128 v[130:133], v182 offset:44560
	v_add_f32_dpp v154, v154, v154 row_mirror row_mask:0xf bank_mask:0xf bound_ctrl:1
	ds_read_b64 v[236:237], v182 offset:44576
	ds_read_b128 v[134:137], v183 offset:44544
	v_pk_fma_f32 v[142:143], v[154:155], v[194:195], v[142:143] op_sel_hi:[0,1,1]
	v_pk_fma_f32 v[144:145], v[154:155], v[202:203], v[144:145] op_sel_hi:[0,1,1]
	ds_read_b128 v[222:225], v183 offset:44560
	ds_read_b64 v[238:239], v183 offset:44576
	ds_read_b32 v242, v186 offset:1856
	s_waitcnt lgkmcnt(7)
	v_pk_mul_f32 v[150:151], v[142:143], v[206:207]
	v_pk_fma_f32 v[150:151], v[144:145], v[214:215], v[150:151]
	v_pk_mul_f32 v[152:153], v[142:143], v[228:229]
	v_add_f32_e32 v154, v150, v151
	v_pk_fma_f32 v[152:153], v[144:145], v[230:231], v[152:153]
	v_pk_mul_f32 v[146:147], v[142:143], v[208:209]
	v_add_f32_dpp v154, v154, v154 quad_perm:[1,0,3,2] row_mask:0xf bank_mask:0xf bound_ctrl:1
	v_pk_mul_f32 v[148:149], v[144:145], v[216:217]
	v_add_f32_e32 v167, v152, v153
	v_add_f32_dpp v154, v154, v154 quad_perm:[2,3,0,1] row_mask:0xf bank_mask:0xf bound_ctrl:1
	v_pk_fma_f32 v[146:147], v[240:241], v[212:213], v[146:147] op_sel:[1,0,0] op_sel_hi:[1,1,1]
	v_pk_fma_f32 v[148:149], v[240:241], v[220:221], v[148:149] op_sel:[1,0,0] op_sel_hi:[1,1,1]
	v_add_f32_dpp v154, v154, v154 row_half_mirror row_mask:0xf bank_mask:0xf bound_ctrl:1
	ds_read_b128 v[190:193], v182 offset:46080
	ds_read_b128 v[194:197], v182 offset:46096
	v_add_f32_dpp v154, v154, v154 row_mirror row_mask:0xf bank_mask:0xf bound_ctrl:1
	ds_read_b64 v[228:229], v182 offset:46112
	ds_read_b128 v[198:201], v183 offset:46080
	v_pk_fma_f32 v[146:147], v[154:155], v[210:211], v[146:147] op_sel_hi:[0,1,1]
	v_pk_fma_f32 v[148:149], v[154:155], v[218:219], v[148:149] op_sel_hi:[0,1,1]
	ds_read_b128 v[202:205], v183 offset:46096
	ds_read_b64 v[230:231], v183 offset:46112
	ds_read_b32 v240, v186 offset:1920
	s_waitcnt lgkmcnt(7)
	v_pk_mul_f32 v[150:151], v[146:147], v[126:127]
	v_pk_fma_f32 v[150:151], v[148:149], v[134:135], v[150:151]
	v_pk_mul_f32 v[152:153], v[146:147], v[232:233]
	v_add_f32_e32 v154, v150, v151
	v_pk_fma_f32 v[152:153], v[148:149], v[234:235], v[152:153]
	v_pk_mul_f32 v[142:143], v[146:147], v[128:129]
	v_add_f32_dpp v154, v154, v154 quad_perm:[1,0,3,2] row_mask:0xf bank_mask:0xf bound_ctrl:1
	v_pk_mul_f32 v[144:145], v[148:149], v[136:137]
	v_add_f32_e32 v168, v152, v153
	v_add_f32_dpp v154, v154, v154 quad_perm:[2,3,0,1] row_mask:0xf bank_mask:0xf bound_ctrl:1
	v_pk_fma_f32 v[142:143], v[242:243], v[132:133], v[142:143] op_sel:[0,0,0] op_sel_hi:[0,1,1]
	v_pk_fma_f32 v[144:145], v[242:243], v[224:225], v[144:145] op_sel:[0,0,0] op_sel_hi:[0,1,1]
	v_add_f32_dpp v154, v154, v154 row_half_mirror row_mask:0xf bank_mask:0xf bound_ctrl:1
	ds_read_b128 v[206:209], v182 offset:47616
	ds_read_b128 v[210:213], v182 offset:47632
	v_add_f32_dpp v154, v154, v154 row_mirror row_mask:0xf bank_mask:0xf bound_ctrl:1
	ds_read_b64 v[232:233], v182 offset:47648
	ds_read_b128 v[214:217], v183 offset:47616
	v_pk_fma_f32 v[142:143], v[154:155], v[130:131], v[142:143] op_sel_hi:[0,1,1]
	v_pk_fma_f32 v[144:145], v[154:155], v[222:223], v[144:145] op_sel_hi:[0,1,1]
	ds_read_b128 v[218:221], v183 offset:47632
	ds_read_b64 v[234:235], v183 offset:47648
	ds_read_b32 v241, v186 offset:1984
	s_waitcnt lgkmcnt(7)
; __device__ __forceinline__ void wkv_phase(const WkvT& W, unsigned char* lds) {
;     ...
;                 for (int t = 0; t < 32; ++t) {
;                     const f32x2 a2 = {nA[0], nA[1]}, w2 = {nA[2], nA[3]}, b2 = {nB[0], nB[1]}, k2 = {nB[2], nB[3]}, r2 = nr; const float v = nv;
;                     if (t + 1 < 32) { nA = *(const f32x4*)(pp + (t + 1) * 384); nB = *(const f32x4*)(pp + (t + 1) * 384 + 4); nr = *(const f32x2*)(pp + (t + 1) * 384 + 8); nv = pv[(t + 1) * 16]; }
;                     float S0 = S.x, S1 = S.y;
;                     float d = S0 * a2.x; d = __builtin_fmaf(S1, a2.y, d);
;                     float t0 = S0 * w2.x; t0 = __builtin_fmaf(v, k2.x, t0); asm volatile("" : "+v"(t0));
;                     float t1 = S1 * w2.y; t1 = __builtin_fmaf(v, k2.y, t1); asm volatile("" : "+v"(t1));
;                     float yprev; const float sa = wkv_reduce(d, ep, yprev);
;                     S0 = __builtin_fmaf(sa, b2.x, t0); asm volatile("" : "+v"(S0));
;                     S1 = __builtin_fmaf(sa, b2.y, t1); asm volatile("" : "+v"(S1));
;                     ep = S0 * r2.x; ep = __builtin_fmaf(S1, r2.y, ep);
;                     S.x = S0; S.y = S1;
;                     if (t >= 1) { const bool hit = oddrow && ((lane & 15) == ((t - 1) & 15)); if (t <= 16) yk0 = hit ? yprev : yk0; else yk1 = hit ? yprev : yk1; }
;                 }
;                 { float ylast; (void)wkv_reduce(0.f, ep, ylast); yk1 = (oddrow && (lane & 15) == 15) ? ylast : yk1; }
;                 if (oddrow) { sY[bi * 512 + (lane & 15) * 16 + il] = yk0; sY[bi * 512 + (16 + (lane & 15)) * 16 + il] = yk1; }
	v_pk_mul_f32 v[150:151], v[142:143], v[190:191]
	v_pk_fma_f32 v[150:151], v[144:145], v[198:199], v[150:151]
	v_pk_mul_f32 v[152:153], v[142:143], v[236:237]
	v_add_f32_e32 v154, v150, v151
	v_pk_fma_f32 v[152:153], v[144:145], v[238:239], v[152:153]
	v_pk_mul_f32 v[146:147], v[142:143], v[192:193]
	v_add_f32_dpp v154, v154, v154 quad_perm:[1,0,3,2] row_mask:0xf bank_mask:0xf bound_ctrl:1
	v_pk_mul_f32 v[148:149], v[144:145], v[200:201]
	v_add_f32_e32 v169, v152, v153
	v_add_f32_dpp v154, v154, v154 quad_perm:[2,3,0,1] row_mask:0xf bank_mask:0xf bound_ctrl:1
	v_pk_fma_f32 v[146:147], v[240:241], v[196:197], v[146:147] op_sel:[0,0,0] op_sel_hi:[0,1,1]
	v_pk_fma_f32 v[148:149], v[240:241], v[204:205], v[148:149] op_sel:[0,0,0] op_sel_hi:[0,1,1]
	v_add_f32_dpp v154, v154, v154 row_half_mirror row_mask:0xf bank_mask:0xf bound_ctrl:1
	s_nop 1
	v_add_f32_dpp v154, v154, v154 row_mirror row_mask:0xf bank_mask:0xf bound_ctrl:1
	v_pk_fma_f32 v[146:147], v[154:155], v[194:195], v[146:147] op_sel_hi:[0,1,1]
	v_pk_fma_f32 v[148:149], v[154:155], v[202:203], v[148:149] op_sel_hi:[0,1,1]
	s_waitcnt lgkmcnt(0)
	v_pk_mul_f32 v[150:151], v[146:147], v[206:207]
	v_pk_fma_f32 v[150:151], v[148:149], v[214:215], v[150:151]
	v_pk_mul_f32 v[152:153], v[146:147], v[228:229]
	v_add_f32_e32 v154, v150, v151
	v_pk_fma_f32 v[152:153], v[148:149], v[230:231], v[152:153]
	v_pk_mul_f32 v[142:143], v[146:147], v[208:209]
	v_add_f32_dpp v154, v154, v154 quad_perm:[1,0,3,2] row_mask:0xf bank_mask:0xf bound_ctrl:1
	v_pk_mul_f32 v[144:145], v[148:149], v[216:217]
	v_add_f32_e32 v170, v152, v153
	v_add_f32_dpp v154, v154, v154 quad_perm:[2,3,0,1] row_mask:0xf bank_mask:0xf bound_ctrl:1
	v_pk_fma_f32 v[142:143], v[240:241], v[212:213], v[142:143] op_sel:[1,0,0] op_sel_hi:[1,1,1]
	v_pk_fma_f32 v[144:145], v[240:241], v[220:221], v[144:145] op_sel:[1,0,0] op_sel_hi:[1,1,1]
	v_add_f32_dpp v154, v154, v154 row_half_mirror row_mask:0xf bank_mask:0xf bound_ctrl:1
	s_nop 1
	v_add_f32_dpp v154, v154, v154 row_mirror row_mask:0xf bank_mask:0xf bound_ctrl:1
	v_pk_fma_f32 v[142:143], v[154:155], v[210:211], v[142:143] op_sel_hi:[0,1,1]
	v_pk_fma_f32 v[144:145], v[154:155], v[218:219], v[144:145] op_sel_hi:[0,1,1]
	v_pk_mul_f32 v[152:153], v[142:143], v[232:233]
	v_pk_fma_f32 v[152:153], v[144:145], v[234:235], v[152:153]
	s_nop 0
	v_add_f32_e32 v171, v152, v153
	v_add_f32_dpp v172, v156, v156 row_ror:8 row_mask:0xf bank_mask:0x3
	v_add_f32_dpp v172, v164, v164 row_ror:8 row_mask:0xf bank_mask:0xc
	v_add_f32_dpp v173, v157, v157 row_ror:8 row_mask:0xf bank_mask:0x3
	v_add_f32_dpp v173, v165, v165 row_ror:8 row_mask:0xf bank_mask:0xc
	v_add_f32_dpp v174, v158, v158 row_ror:8 row_mask:0xf bank_mask:0x3
	v_add_f32_dpp v174, v166, v166 row_ror:8 row_mask:0xf bank_mask:0xc
	v_add_f32_dpp v175, v159, v159 row_ror:8 row_mask:0xf bank_mask:0x3
	v_add_f32_dpp v175, v167, v167 row_ror:8 row_mask:0xf bank_mask:0xc
	v_add_f32_dpp v176, v160, v160 row_ror:8 row_mask:0xf bank_mask:0x3
	v_add_f32_dpp v176, v168, v168 row_ror:8 row_mask:0xf bank_mask:0xc
	v_add_f32_dpp v177, v161, v161 row_ror:8 row_mask:0xf bank_mask:0x3
	v_add_f32_dpp v177, v169, v169 row_ror:8 row_mask:0xf bank_mask:0xc
	v_add_f32_dpp v178, v162, v162 row_ror:8 row_mask:0xf bank_mask:0x3
	v_add_f32_dpp v178, v170, v170 row_ror:8 row_mask:0xf bank_mask:0xc
	v_add_f32_dpp v179, v163, v163 row_ror:8 row_mask:0xf bank_mask:0x3
	v_add_f32_dpp v179, v171, v171 row_ror:8 row_mask:0xf bank_mask:0xc
	v_add_f32_dpp v156, v172, v172 row_half_mirror row_mask:0xf bank_mask:0x5
	v_add_f32_dpp v156, v176, v176 row_half_mirror row_mask:0xf bank_mask:0xa
	v_add_f32_dpp v157, v173, v173 row_half_mirror row_mask:0xf bank_mask:0x5
	v_add_f32_dpp v157, v177, v177 row_half_mirror row_mask:0xf bank_mask:0xa
	v_add_f32_dpp v158, v174, v174 row_half_mirror row_mask:0xf bank_mask:0x5
	v_add_f32_dpp v158, v178, v178 row_half_mirror row_mask:0xf bank_mask:0xa
	v_add_f32_dpp v159, v175, v175 row_half_mirror row_mask:0xf bank_mask:0x5
	v_add_f32_dpp v159, v179, v179 row_half_mirror row_mask:0xf bank_mask:0xa
	v_cndmask_b32_e64 v176, v158, v156, s[14:15]
	v_cndmask_b32_e64 v177, v159, v157, s[14:15]
	v_cndmask_b32_e64 v178, v156, v158, s[14:15]
	v_cndmask_b32_e64 v179, v157, v159, s[14:15]
	v_add_f32_dpp v172, v176, v178 quad_perm:[2,3,0,1] row_mask:0xf bank_mask:0xf
	v_add_f32_dpp v173, v177, v179 quad_perm:[2,3,0,1] row_mask:0xf bank_mask:0xf
	v_cndmask_b32_e64 v176, v173, v172, s[16:17]
	v_cndmask_b32_e64 v178, v172, v173, s[16:17]
	s_nop 0
	v_add_f32_dpp v181, v176, v178 quad_perm:[1,0,3,2] row_mask:0xf bank_mask:0xf
	ds_write2st64_b32 v187, v180, v181 offset0:0 offset1:4

; __device__ __forceinline__ void wkv_phase(const WkvT& W, unsigned char* lds) {
;     ...
;         for (int c = 0; c < 256; ++c) {
;             const int bi = c & 1, bo = bi * 12288, bn = (bi ^ 1) * 12288;
;             if (c + 1 < 256) wkv_issue(W, raw, rowbase, cbase, q, c + 1, tid);
;             {
;                 const float* pp = sP + bo + jj * 12;
;                 const float* pv = sV + bi * 512 + il;
;                 f32x4 nA = *(const f32x4*)pp, nB = *(const f32x4*)(pp + 4); f32x2 nr = *(const f32x2*)(pp + 8); float nv = pv[0];
;                 float yk0 = 0.f, yk1 = 0.f, ep = 0.f;
;                 const bool oddrow = (lane & 16) != 0;
; #pragma unroll
;                 for (int t = 0; t < 32; ++t) {
;                     const f32x2 a2 = {nA[0], nA[1]}, w2 = {nA[2], nA[3]}, b2 = {nB[0], nB[1]}, k2 = {nB[2], nB[3]}, r2 = nr; const float v = nv;
;                     if (t + 1 < 32) { nA = *(const f32x4*)(pp + (t + 1) * 384); nB = *(const f32x4*)(pp + (t + 1) * 384 + 4); nr = *(const f32x2*)(pp + (t + 1) * 384 + 8); nv = pv[(t + 1) * 16]; }
.LBB0_1636:
	s_bitcmp1_b32 s99, 8
	s_cbranch_scc1 .Lwkv4_b2_skip
	ds_read_b128 v[190:193], v182 offset:49152
	ds_read_b128 v[194:197], v182 offset:49168
	ds_read_b64 v[228:229], v182 offset:49184
	ds_read_b128 v[198:201], v183 offset:49152
	ds_read_b128 v[202:205], v183 offset:49168
	ds_read_b64 v[230:231], v183 offset:49184
	ds_read_b32 v240, v186 offset:2048
	ds_read_b128 v[206:209], v182 offset:50688
	ds_read_b128 v[210:213], v182 offset:50704
	ds_read_b64 v[232:233], v182 offset:50720
	ds_read_b128 v[214:217], v183 offset:50688
	ds_read_b128 v[218:221], v183 offset:50704
	ds_read_b64 v[234:235], v183 offset:50720
	ds_read_b32 v241, v186 offset:2112
	s_waitcnt lgkmcnt(7)
	v_pk_mul_f32 v[150:151], v[142:143], v[190:191]
	v_pk_fma_f32 v[150:151], v[144:145], v[198:199], v[150:151]
	v_pk_mul_f32 v[146:147], v[142:143], v[192:193]
	v_add_f32_e32 v154, v150, v151
	v_pk_mul_f32 v[148:149], v[144:145], v[200:201]
	v_pk_fma_f32 v[146:147], v[240:241], v[196:197], v[146:147] op_sel:[0,0,0] op_sel_hi:[0,1,1]
	v_add_f32_dpp v154, v154, v154 quad_perm:[1,0,3,2] row_mask:0xf bank_mask:0xf bound_ctrl:1
	v_pk_fma_f32 v[148:149], v[240:241], v[204:205], v[148:149] op_sel:[0,0,0] op_sel_hi:[0,1,1]
	s_nop 0
	v_add_f32_dpp v154, v154, v154 quad_perm:[2,3,0,1] row_mask:0xf bank_mask:0xf bound_ctrl:1
	ds_read_b128 v[126:129], v182 offset:52224
	ds_read_b128 v[130:133], v182 offset:52240
	v_add_f32_dpp v154, v154, v154 row_half_mirror row_mask:0xf bank_mask:0xf bound_ctrl:1
	ds_read_b64 v[236:237], v182 offset:52256
	ds_read_b128 v[134:137], v183 offset:52224
	v_add_f32_dpp v154, v154, v154 row_mirror row_mask:0xf bank_mask:0xf bound_ctrl:1
	v_pk_fma_f32 v[146:147], v[154:155], v[194:195], v[146:147] op_sel_hi:[0,1,1]
	v_pk_fma_f32 v[148:149], v[154:155], v[202:203], v[148:149] op_sel_hi:[0,1,1]
	ds_read_b128 v[222:225], v183 offset:52240
	ds_read_b64 v[238:239], v183 offset:52256
	ds_read_b32 v242, v186 offset:2176
	s_waitcnt lgkmcnt(7)
	v_pk_mul_f32 v[150:151], v[146:147], v[206:207]
	v_pk_fma_f32 v[150:151], v[148:149], v[214:215], v[150:151]
	v_pk_mul_f32 v[152:153], v[146:147], v[228:229]
	v_add_f32_e32 v154, v150, v151
	v_pk_fma_f32 v[152:153], v[148:149], v[230:231], v[152:153]
	v_pk_mul_f32 v[142:143], v[146:147], v[208:209]
	v_add_f32_dpp v154, v154, v154 quad_perm:[1,0,3,2] row_mask:0xf bank_mask:0xf bound_ctrl:1
	v_pk_mul_f32 v[144:145], v[148:149], v[216:217]
	v_add_f32_e32 v156, v152, v153
	v_add_f32_dpp v154, v154, v154 quad_perm:[2,3,0,1] row_mask:0xf bank_mask:0xf bound_ctrl:1
	v_pk_fma_f32 v[142:143], v[240:241], v[212:213], v[142:143] op_sel:[1,0,0] op_sel_hi:[1,1,1]
	v_pk_fma_f32 v[144:145], v[240:241], v[220:221], v[144:145] op_sel:[1,0,0] op_sel_hi:[1,1,1]
	v_add_f32_dpp v154, v154, v154 row_half_mirror row_mask:0xf bank_mask:0xf bound_ctrl:1
	ds_read_b128 v[190:193], v182 offset:53760
	ds_read_b128 v[194:197], v182 offset:53776
	v_add_f32_dpp v154, v154, v154 row_mirror row_mask:0xf bank_mask:0xf bound_ctrl:1
	ds_read_b64 v[228:229], v182 offset:53792
	ds_read_b128 v[198:201], v183 offset:53760
	v_pk_fma_f32 v[142:143], v[154:155], v[210:211], v[142:143] op_sel_hi:[0,1,1]
	v_pk_fma_f32 v[144:145], v[154:155], v[218:219], v[144:145] op_sel_hi:[0,1,1]
	ds_read_b128 v[202:205], v183 offset:53776
	ds_read_b64 v[230:231], v183 offset:53792
	ds_read_b32 v240, v186 offset:2240
	s_waitcnt lgkmcnt(7)
	v_pk_mul_f32 v[150:151], v[142:143], v[126:127]
	v_pk_fma_f32 v[150:151], v[144:145], v[134:135], v[150:151]
	v_pk_mul_f32 v[152:153], v[142:143], v[232:233]
	v_add_f32_e32 v154, v150, v151
	v_pk_fma_f32 v[152:153], v[144:145], v[234:235], v[152:153]
	v_pk_mul_f32 v[146:147], v[142:143], v[128:129]
	v_add_f32_dpp v154, v154, v154 quad_perm:[1,0,3,2] row_mask:0xf bank_mask:0xf bound_ctrl:1
	v_pk_mul_f32 v[148:149], v[144:145], v[136:137]
	v_add_f32_e32 v157, v152, v153
	v_add_f32_dpp v154, v154, v154 quad_perm:[2,3,0,1] row_mask:0xf bank_mask:0xf bound_ctrl:1
	v_pk_fma_f32 v[146:147], v[242:243], v[132:133], v[146:147] op_sel:[0,0,0] op_sel_hi:[0,1,1]
	v_pk_fma_f32 v[148:149], v[242:243], v[224:225], v[148:149] op_sel:[0,0,0] op_sel_hi:[0,1,1]
	v_add_f32_dpp v154, v154, v154 row_half_mirror row_mask:0xf bank_mask:0xf bound_ctrl:1
	ds_read_b128 v[206:209], v182 offset:55296
	ds_read_b128 v[210:213], v182 offset:55312
	v_add_f32_dpp v154, v154, v154 row_mirror row_mask:0xf bank_mask:0xf bound_ctrl:1
	ds_read_b64 v[232:233], v182 offset:55328
	ds_read_b128 v[214:217], v183 offset:55296
	v_pk_fma_f32 v[146:147], v[154:155], v[130:131], v[146:147] op_sel_hi:[0,1,1]
	v_pk_fma_f32 v[148:149], v[154:155], v[222:223], v[148:149] op_sel_hi:[0,1,1]
	ds_read_b128 v[218:221], v183 offset:55312
	ds_read_b64 v[234:235], v183 offset:55328
	ds_read_b32 v241, v186 offset:2304
	s_waitcnt lgkmcnt(7)
	v_pk_mul_f32 v[150:151], v[146:147], v[190:191]
	v_pk_fma_f32 v[150:151], v[148:149], v[198:199], v[150:151]
	v_pk_mul_f32 v[152:153], v[146:147], v[236:237]
	v_add_f32_e32 v154, v150, v151
	v_pk_fma_f32 v[152:153], v[148:149], v[238:239], v[152:153]
	v_pk_mul_f32 v[142:143], v[146:147], v[192:193]
	v_add_f32_dpp v154, v154, v154 quad_perm:[1,0,3,2] row_mask:0xf bank_mask:0xf bound_ctrl:1
	v_pk_mul_f32 v[144:145], v[148:149], v[200:201]
	v_add_f32_e32 v158, v152, v153
	v_add_f32_dpp v154, v154, v154 quad_perm:[2,3,0,1] row_mask:0xf bank_mask:0xf bound_ctrl:1
	v_pk_fma_f32 v[142:143], v[240:241], v[196:197], v[142:143] op_sel:[0,0,0] op_sel_hi:[0,1,1]
	v_pk_fma_f32 v[144:145], v[240:241], v[204:205], v[144:145] op_sel:[0,0,0] op_sel_hi:[0,1,1]
	v_add_f32_dpp v154, v154, v154 row_half_mirror row_mask:0xf bank_mask:0xf bound_ctrl:1
	ds_read_b128 v[126:129], v182 offset:56832
	ds_read_b128 v[130:133], v182 offset:56848
	v_add_f32_dpp v154, v154, v154 row_mirror row_mask:0xf bank_mask:0xf bound_ctrl:1
	ds_read_b64 v[236:237], v182 offset:56864
	ds_read_b128 v[134:137], v183 offset:56832
	v_pk_fma_f32 v[142:143], v[154:155], v[194:195], v[142:143] op_sel_hi:[0,1,1]
	v_pk_fma_f32 v[144:145], v[154:155], v[202:203], v[144:145] op_sel_hi:[0,1,1]
	ds_read_b128 v[222:225], v183 offset:56848
	ds_read_b64 v[238:239], v183 offset:56864
	ds_read_b32 v242, v186 offset:2368
	s_waitcnt lgkmcnt(7)
; __device__ __forceinline__ void wkv_phase(const WkvT& W, unsigned char* lds) {
;     ...
;                 const float* pp = sP + bo + jj * 12;
;                 const float* pv = sV + bi * 512 + il;
;                 f32x4 nA = *(const f32x4*)pp, nB = *(const f32x4*)(pp + 4); f32x2 nr = *(const f32x2*)(pp + 8); float nv = pv[0];
;                 float yk0 = 0.f, yk1 = 0.f, ep = 0.f;
;                 const bool oddrow = (lane & 16) != 0;
; #pragma unroll
;                 for (int t = 0; t < 32; ++t) {
;                     const f32x2 a2 = {nA[0], nA[1]}, w2 = {nA[2], nA[3]}, b2 = {nB[0], nB[1]}, k2 = {nB[2], nB[3]}, r2 = nr; const float v = nv;
;                     if (t + 1 < 32) { nA = *(const f32x4*)(pp + (t + 1) * 384); nB = *(const f32x4*)(pp + (t + 1) * 384 + 4); nr = *(const f32x2*)(pp + (t + 1) * 384 + 8); nv = pv[(t + 1) * 16]; }
;                     float S0 = S.x, S1 = S.y;
;                     float d = S0 * a2.x; d = __builtin_fmaf(S1, a2.y, d);
;                     float t0 = S0 * w2.x; t0 = __builtin_fmaf(v, k2.x, t0); asm volatile("" : "+v"(t0));
;                     float t1 = S1 * w2.y; t1 = __builtin_fmaf(v, k2.y, t1); asm volatile("" : "+v"(t1));
;                     float yprev; const float sa = wkv_reduce(d, ep, yprev);
;                     S0 = __builtin_fmaf(sa, b2.x, t0); asm volatile("" : "+v"(S0));
;                     S1 = __builtin_fmaf(sa, b2.y, t1); asm volatile("" : "+v"(S1));
;                     ep = S0 * r2.x; ep = __builtin_fmaf(S1, r2.y, ep);
;                     S.x = S0; S.y = S1;
;                     if (t >= 1) { const bool hit = oddrow && ((lane & 15) == ((t - 1) & 15)); if (t <= 16) yk0 = hit ? yprev : yk0; else yk1 = hit ? yprev : yk1; }
;                 }
	v_pk_mul_f32 v[150:151], v[142:143], v[206:207]
	v_pk_fma_f32 v[150:151], v[144:145], v[214:215], v[150:151]
	v_pk_mul_f32 v[152:153], v[142:143], v[228:229]
	v_add_f32_e32 v154, v150, v151
	v_pk_fma_f32 v[152:153], v[144:145], v[230:231], v[152:153]
	v_pk_mul_f32 v[146:147], v[142:143], v[208:209]
	v_add_f32_dpp v154, v154, v154 quad_perm:[1,0,3,2] row_mask:0xf bank_mask:0xf bound_ctrl:1
	v_pk_mul_f32 v[148:149], v[144:145], v[216:217]
	v_add_f32_e32 v159, v152, v153
	v_add_f32_dpp v154, v154, v154 quad_perm:[2,3,0,1] row_mask:0xf bank_mask:0xf bound_ctrl:1
	v_pk_fma_f32 v[146:147], v[240:241], v[212:213], v[146:147] op_sel:[1,0,0] op_sel_hi:[1,1,1]
	v_pk_fma_f32 v[148:149], v[240:241], v[220:221], v[148:149] op_sel:[1,0,0] op_sel_hi:[1,1,1]
	v_add_f32_dpp v154, v154, v154 row_half_mirror row_mask:0xf bank_mask:0xf bound_ctrl:1
	ds_read_b128 v[190:193], v182 offset:58368
	ds_read_b128 v[194:197], v182 offset:58384
	v_add_f32_dpp v154, v154, v154 row_mirror row_mask:0xf bank_mask:0xf bound_ctrl:1
	ds_read_b64 v[228:229], v182 offset:58400
	ds_read_b128 v[198:201], v183 offset:58368
	v_pk_fma_f32 v[146:147], v[154:155], v[210:211], v[146:147] op_sel_hi:[0,1,1]
	v_pk_fma_f32 v[148:149], v[154:155], v[218:219], v[148:149] op_sel_hi:[0,1,1]
	ds_read_b128 v[202:205], v183 offset:58384
	ds_read_b64 v[230:231], v183 offset:58400
	ds_read_b32 v240, v186 offset:2432
	s_waitcnt lgkmcnt(7)
	v_pk_mul_f32 v[150:151], v[146:147], v[126:127]
	v_pk_fma_f32 v[150:151], v[148:149], v[134:135], v[150:151]
	v_pk_mul_f32 v[152:153], v[146:147], v[232:233]
	v_add_f32_e32 v154, v150, v151
	v_pk_fma_f32 v[152:153], v[148:149], v[234:235], v[152:153]
	v_pk_mul_f32 v[142:143], v[146:147], v[128:129]
	v_add_f32_dpp v154, v154, v154 quad_perm:[1,0,3,2] row_mask:0xf bank_mask:0xf bound_ctrl:1
	v_pk_mul_f32 v[144:145], v[148:149], v[136:137]
	v_add_f32_e32 v160, v152, v153
	v_add_f32_dpp v154, v154, v154 quad_perm:[2,3,0,1] row_mask:0xf bank_mask:0xf bound_ctrl:1
	v_pk_fma_f32 v[142:143], v[242:243], v[132:133], v[142:143] op_sel:[0,0,0] op_sel_hi:[0,1,1]
	v_pk_fma_f32 v[144:145], v[242:243], v[224:225], v[144:145] op_sel:[0,0,0] op_sel_hi:[0,1,1]
	v_add_f32_dpp v154, v154, v154 row_half_mirror row_mask:0xf bank_mask:0xf bound_ctrl:1
	ds_read_b128 v[206:209], v182 offset:59904
	ds_read_b128 v[210:213], v182 offset:59920
	v_add_f32_dpp v154, v154, v154 row_mirror row_mask:0xf bank_mask:0xf bound_ctrl:1
	ds_read_b64 v[232:233], v182 offset:59936
	ds_read_b128 v[214:217], v183 offset:59904
	v_pk_fma_f32 v[142:143], v[154:155], v[130:131], v[142:143] op_sel_hi:[0,1,1]
	v_pk_fma_f32 v[144:145], v[154:155], v[222:223], v[144:145] op_sel_hi:[0,1,1]
	ds_read_b128 v[218:221], v183 offset:59920
	ds_read_b64 v[234:235], v183 offset:59936
	ds_read_b32 v241, v186 offset:2496
	s_waitcnt lgkmcnt(7)
	v_pk_mul_f32 v[150:151], v[142:143], v[190:191]
	v_pk_fma_f32 v[150:151], v[144:145], v[198:199], v[150:151]
	v_pk_mul_f32 v[152:153], v[142:143], v[236:237]
	v_add_f32_e32 v154, v150, v151
	v_pk_fma_f32 v[152:153], v[144:145], v[238:239], v[152:153]
	v_pk_mul_f32 v[146:147], v[142:143], v[192:193]
	v_add_f32_dpp v154, v154, v154 quad_perm:[1,0,3,2] row_mask:0xf bank_mask:0xf bound_ctrl:1
	v_pk_mul_f32 v[148:149], v[144:145], v[200:201]
	v_add_f32_e32 v161, v152, v153
	v_add_f32_dpp v154, v154, v154 quad_perm:[2,3,0,1] row_mask:0xf bank_mask:0xf bound_ctrl:1
	v_pk_fma_f32 v[146:147], v[240:241], v[196:197], v[146:147] op_sel:[0,0,0] op_sel_hi:[0,1,1]
	v_pk_fma_f32 v[148:149], v[240:241], v[204:205], v[148:149] op_sel:[0,0,0] op_sel_hi:[0,1,1]
	v_add_f32_dpp v154, v154, v154 row_half_mirror row_mask:0xf bank_mask:0xf bound_ctrl:1
	ds_read_b128 v[126:129], v182 offset:61440
	ds_read_b128 v[130:133], v182 offset:61456
	v_add_f32_dpp v154, v154, v154 row_mirror row_mask:0xf bank_mask:0xf bound_ctrl:1
	ds_read_b64 v[236:237], v182 offset:61472
	ds_read_b128 v[134:137], v183 offset:61440
	v_pk_fma_f32 v[146:147], v[154:155], v[194:195], v[146:147] op_sel_hi:[0,1,1]
	v_pk_fma_f32 v[148:149], v[154:155], v[202:203], v[148:149] op_sel_hi:[0,1,1]
	ds_read_b128 v[222:225], v183 offset:61456
	ds_read_b64 v[238:239], v183 offset:61472
	ds_read_b32 v242, v186 offset:2560
	s_waitcnt lgkmcnt(7)
	v_pk_mul_f32 v[150:151], v[146:147], v[206:207]
	v_pk_fma_f32 v[150:151], v[148:149], v[214:215], v[150:151]
	v_pk_mul_f32 v[152:153], v[146:147], v[228:229]
	v_add_f32_e32 v154, v150, v151
	v_pk_fma_f32 v[152:153], v[148:149], v[230:231], v[152:153]
	v_pk_mul_f32 v[142:143], v[146:147], v[208:209]
	v_add_f32_dpp v154, v154, v154 quad_perm:[1,0,3,2] row_mask:0xf bank_mask:0xf bound_ctrl:1
	v_pk_mul_f32 v[144:145], v[148:149], v[216:217]
	v_add_f32_e32 v162, v152, v153
	v_add_f32_dpp v154, v154, v154 quad_perm:[2,3,0,1] row_mask:0xf bank_mask:0xf bound_ctrl:1
	v_pk_fma_f32 v[142:143], v[240:241], v[212:213], v[142:143] op_sel:[1,0,0] op_sel_hi:[1,1,1]
	v_pk_fma_f32 v[144:145], v[240:241], v[220:221], v[144:145] op_sel:[1,0,0] op_sel_hi:[1,1,1]
	v_add_f32_dpp v154, v154, v154 row_half_mirror row_mask:0xf bank_mask:0xf bound_ctrl:1
	ds_read_b128 v[190:193], v182 offset:62976
	ds_read_b128 v[194:197], v182 offset:62992
	v_add_f32_dpp v154, v154, v154 row_mirror row_mask:0xf bank_mask:0xf bound_ctrl:1
	ds_read_b64 v[228:229], v182 offset:63008
	ds_read_b128 v[198:201], v183 offset:62976
	v_pk_fma_f32 v[142:143], v[154:155], v[210:211], v[142:143] op_sel_hi:[0,1,1]
	v_pk_fma_f32 v[144:145], v[154:155], v[218:219], v[144:145] op_sel_hi:[0,1,1]
	ds_read_b128 v[202:205], v183 offset:62992
	ds_read_b64 v[230:231], v183 offset:63008
	ds_read_b32 v240, v186 offset:2624
	s_waitcnt lgkmcnt(7)
; __device__ __forceinline__ void wkv_phase(const WkvT& W, unsigned char* lds) {
;     ...
;                 const float* pp = sP + bo + jj * 12;
;                 const float* pv = sV + bi * 512 + il;
;                 f32x4 nA = *(const f32x4*)pp, nB = *(const f32x4*)(pp + 4); f32x2 nr = *(const f32x2*)(pp + 8); float nv = pv[0];
;                 float yk0 = 0.f, yk1 = 0.f, ep = 0.f;
;                 const bool oddrow = (lane & 16) != 0;
; #pragma unroll
;                 for (int t = 0; t < 32; ++t) {
;                     const f32x2 a2 = {nA[0], nA[1]}, w2 = {nA[2], nA[3]}, b2 = {nB[0], nB[1]}, k2 = {nB[2], nB[3]}, r2 = nr; const float v = nv;
;                     if (t + 1 < 32) { nA = *(const f32x4*)(pp + (t + 1) * 384); nB = *(const f32x4*)(pp + (t + 1) * 384 + 4); nr = *(const f32x2*)(pp + (t + 1) * 384 + 8); nv = pv[(t + 1) * 16]; }
;                     float S0 = S.x, S1 = S.y;
;                     float d = S0 * a2.x; d = __builtin_fmaf(S1, a2.y, d);
;                     float t0 = S0 * w2.x; t0 = __builtin_fmaf(v, k2.x, t0); asm volatile("" : "+v"(t0));
;                     float t1 = S1 * w2.y; t1 = __builtin_fmaf(v, k2.y, t1); asm volatile("" : "+v"(t1));
;                     float yprev; const float sa = wkv_reduce(d, ep, yprev);
;                     S0 = __builtin_fmaf(sa, b2.x, t0); asm volatile("" : "+v"(S0));
;                     S1 = __builtin_fmaf(sa, b2.y, t1); asm volatile("" : "+v"(S1));
;                     ep = S0 * r2.x; ep = __builtin_fmaf(S1, r2.y, ep);
;                     S.x = S0; S.y = S1;
;                     if (t >= 1) { const bool hit = oddrow && ((lane & 15) == ((t - 1) & 15)); if (t <= 16) yk0 = hit ? yprev : yk0; else yk1 = hit ? yprev : yk1; }
;                 }
	v_pk_mul_f32 v[150:151], v[142:143], v[126:127]
	v_pk_fma_f32 v[150:151], v[144:145], v[134:135], v[150:151]
	v_pk_mul_f32 v[152:153], v[142:143], v[232:233]
	v_add_f32_e32 v154, v150, v151
	v_pk_fma_f32 v[152:153], v[144:145], v[234:235], v[152:153]
	v_pk_mul_f32 v[146:147], v[142:143], v[128:129]
	v_add_f32_dpp v154, v154, v154 quad_perm:[1,0,3,2] row_mask:0xf bank_mask:0xf bound_ctrl:1
	v_pk_mul_f32 v[148:149], v[144:145], v[136:137]
	v_add_f32_e32 v163, v152, v153
	v_add_f32_dpp v154, v154, v154 quad_perm:[2,3,0,1] row_mask:0xf bank_mask:0xf bound_ctrl:1
	v_pk_fma_f32 v[146:147], v[242:243], v[132:133], v[146:147] op_sel:[0,0,0] op_sel_hi:[0,1,1]
	v_pk_fma_f32 v[148:149], v[242:243], v[224:225], v[148:149] op_sel:[0,0,0] op_sel_hi:[0,1,1]
	v_add_f32_dpp v154, v154, v154 row_half_mirror row_mask:0xf bank_mask:0xf bound_ctrl:1
	ds_read_b128 v[206:209], v182 offset:64512
	ds_read_b128 v[210:213], v182 offset:64528
	v_add_f32_dpp v154, v154, v154 row_mirror row_mask:0xf bank_mask:0xf bound_ctrl:1
	ds_read_b64 v[232:233], v182 offset:64544
	ds_read_b128 v[214:217], v183 offset:64512
	v_pk_fma_f32 v[146:147], v[154:155], v[130:131], v[146:147] op_sel_hi:[0,1,1]
	v_pk_fma_f32 v[148:149], v[154:155], v[222:223], v[148:149] op_sel_hi:[0,1,1]
	ds_read_b128 v[218:221], v183 offset:64528
	ds_read_b64 v[234:235], v183 offset:64544
	ds_read_b32 v241, v186 offset:2688
	s_waitcnt lgkmcnt(7)
	v_pk_mul_f32 v[150:151], v[146:147], v[190:191]
	v_pk_fma_f32 v[150:151], v[148:149], v[198:199], v[150:151]
	v_pk_mul_f32 v[152:153], v[146:147], v[236:237]
	v_add_f32_e32 v154, v150, v151
	v_pk_fma_f32 v[152:153], v[148:149], v[238:239], v[152:153]
	v_pk_mul_f32 v[142:143], v[146:147], v[192:193]
	v_add_f32_dpp v154, v154, v154 quad_perm:[1,0,3,2] row_mask:0xf bank_mask:0xf bound_ctrl:1
	v_pk_mul_f32 v[144:145], v[148:149], v[200:201]
	v_add_f32_e32 v164, v152, v153
	v_add_f32_dpp v154, v154, v154 quad_perm:[2,3,0,1] row_mask:0xf bank_mask:0xf bound_ctrl:1
	v_pk_fma_f32 v[142:143], v[240:241], v[196:197], v[142:143] op_sel:[0,0,0] op_sel_hi:[0,1,1]
	v_pk_fma_f32 v[144:145], v[240:241], v[204:205], v[144:145] op_sel:[0,0,0] op_sel_hi:[0,1,1]
	v_add_f32_dpp v154, v154, v154 row_half_mirror row_mask:0xf bank_mask:0xf bound_ctrl:1
	ds_read_b128 v[126:129], v184
	ds_read_b128 v[130:133], v184 offset:16
	v_add_f32_dpp v154, v154, v154 row_mirror row_mask:0xf bank_mask:0xf bound_ctrl:1
	ds_read_b64 v[236:237], v184 offset:32
	ds_read_b128 v[134:137], v185
	v_pk_fma_f32 v[142:143], v[154:155], v[194:195], v[142:143] op_sel_hi:[0,1,1]
	v_pk_fma_f32 v[144:145], v[154:155], v[202:203], v[144:145] op_sel_hi:[0,1,1]
	ds_read_b128 v[222:225], v185 offset:16
	ds_read_b64 v[238:239], v185 offset:32
	ds_read_b32 v242, v186 offset:2752
	s_waitcnt lgkmcnt(7)
	v_pk_mul_f32 v[150:151], v[142:143], v[206:207]
	v_pk_fma_f32 v[150:151], v[144:145], v[214:215], v[150:151]
	v_pk_mul_f32 v[152:153], v[142:143], v[228:229]
	v_add_f32_e32 v154, v150, v151
	v_pk_fma_f32 v[152:153], v[144:145], v[230:231], v[152:153]
	v_pk_mul_f32 v[146:147], v[142:143], v[208:209]
	v_add_f32_dpp v154, v154, v154 quad_perm:[1,0,3,2] row_mask:0xf bank_mask:0xf bound_ctrl:1
	v_pk_mul_f32 v[148:149], v[144:145], v[216:217]
	v_add_f32_e32 v165, v152, v153
	v_add_f32_dpp v154, v154, v154 quad_perm:[2,3,0,1] row_mask:0xf bank_mask:0xf bound_ctrl:1
	v_pk_fma_f32 v[146:147], v[240:241], v[212:213], v[146:147] op_sel:[1,0,0] op_sel_hi:[1,1,1]
	v_pk_fma_f32 v[148:149], v[240:241], v[220:221], v[148:149] op_sel:[1,0,0] op_sel_hi:[1,1,1]
	v_add_f32_dpp v154, v154, v154 row_half_mirror row_mask:0xf bank_mask:0xf bound_ctrl:1
	ds_read_b128 v[190:193], v184 offset:1536
	ds_read_b128 v[194:197], v184 offset:1552
	v_add_f32_dpp v154, v154, v154 row_mirror row_mask:0xf bank_mask:0xf bound_ctrl:1
	ds_read_b64 v[228:229], v184 offset:1568
	ds_read_b128 v[198:201], v185 offset:1536
	v_pk_fma_f32 v[146:147], v[154:155], v[210:211], v[146:147] op_sel_hi:[0,1,1]
	v_pk_fma_f32 v[148:149], v[154:155], v[218:219], v[148:149] op_sel_hi:[0,1,1]
	ds_read_b128 v[202:205], v185 offset:1552
	ds_read_b64 v[230:231], v185 offset:1568
	ds_read_b32 v240, v186 offset:2816
	s_waitcnt lgkmcnt(7)
	v_pk_mul_f32 v[150:151], v[146:147], v[126:127]
	v_pk_fma_f32 v[150:151], v[148:149], v[134:135], v[150:151]
	v_pk_mul_f32 v[152:153], v[146:147], v[232:233]
	v_add_f32_e32 v154, v150, v151
	v_pk_fma_f32 v[152:153], v[148:149], v[234:235], v[152:153]
	v_pk_mul_f32 v[142:143], v[146:147], v[128:129]
	v_add_f32_dpp v154, v154, v154 quad_perm:[1,0,3,2] row_mask:0xf bank_mask:0xf bound_ctrl:1
	v_pk_mul_f32 v[144:145], v[148:149], v[136:137]
	v_add_f32_e32 v166, v152, v153
	v_add_f32_dpp v154, v154, v154 quad_perm:[2,3,0,1] row_mask:0xf bank_mask:0xf bound_ctrl:1
	v_pk_fma_f32 v[142:143], v[242:243], v[132:133], v[142:143] op_sel:[0,0,0] op_sel_hi:[0,1,1]
	v_pk_fma_f32 v[144:145], v[242:243], v[224:225], v[144:145] op_sel:[0,0,0] op_sel_hi:[0,1,1]
	v_add_f32_dpp v154, v154, v154 row_half_mirror row_mask:0xf bank_mask:0xf bound_ctrl:1
	ds_read_b128 v[206:209], v184 offset:3072
	ds_read_b128 v[210:213], v184 offset:3088
	v_add_f32_dpp v154, v154, v154 row_mirror row_mask:0xf bank_mask:0xf bound_ctrl:1
	ds_read_b64 v[232:233], v184 offset:3104
	ds_read_b128 v[214:217], v185 offset:3072
	v_pk_fma_f32 v[142:143], v[154:155], v[130:131], v[142:143] op_sel_hi:[0,1,1]
	v_pk_fma_f32 v[144:145], v[154:155], v[222:223], v[144:145] op_sel_hi:[0,1,1]
	ds_read_b128 v[218:221], v185 offset:3088
	ds_read_b64 v[234:235], v185 offset:3104
	ds_read_b32 v241, v186 offset:2880
	s_waitcnt lgkmcnt(7)
; __device__ __forceinline__ void wkv_phase(const WkvT& W, unsigned char* lds) {
;     ...
;                 const float* pp = sP + bo + jj * 12;
;                 const float* pv = sV + bi * 512 + il;
;                 f32x4 nA = *(const f32x4*)pp, nB = *(const f32x4*)(pp + 4); f32x2 nr = *(const f32x2*)(pp + 8); float nv = pv[0];
;                 float yk0 = 0.f, yk1 = 0.f, ep = 0.f;
;                 const bool oddrow = (lane & 16) != 0;
; #pragma unroll
;                 for (int t = 0; t < 32; ++t) {
;                     const f32x2 a2 = {nA[0], nA[1]}, w2 = {nA[2], nA[3]}, b2 = {nB[0], nB[1]}, k2 = {nB[2], nB[3]}, r2 = nr; const float v = nv;
;                     if (t + 1 < 32) { nA = *(const f32x4*)(pp + (t + 1) * 384); nB = *(const f32x4*)(pp + (t + 1) * 384 + 4); nr = *(const f32x2*)(pp + (t + 1) * 384 + 8); nv = pv[(t + 1) * 16]; }
;                     float S0 = S.x, S1 = S.y;
;                     float d = S0 * a2.x; d = __builtin_fmaf(S1, a2.y, d);
;                     float t0 = S0 * w2.x; t0 = __builtin_fmaf(v, k2.x, t0); asm volatile("" : "+v"(t0));
;                     float t1 = S1 * w2.y; t1 = __builtin_fmaf(v, k2.y, t1); asm volatile("" : "+v"(t1));
;                     float yprev; const float sa = wkv_reduce(d, ep, yprev);
;                     S0 = __builtin_fmaf(sa, b2.x, t0); asm volatile("" : "+v"(S0));
;                     S1 = __builtin_fmaf(sa, b2.y, t1); asm volatile("" : "+v"(S1));
;                     ep = S0 * r2.x; ep = __builtin_fmaf(S1, r2.y, ep);
;                     S.x = S0; S.y = S1;
;                     if (t >= 1) { const bool hit = oddrow && ((lane & 15) == ((t - 1) & 15)); if (t <= 16) yk0 = hit ? yprev : yk0; else yk1 = hit ? yprev : yk1; }
;                 }
	v_pk_mul_f32 v[150:151], v[142:143], v[190:191]
	v_pk_fma_f32 v[150:151], v[144:145], v[198:199], v[150:151]
	v_pk_mul_f32 v[152:153], v[142:143], v[236:237]
	v_add_f32_e32 v154, v150, v151
	v_pk_fma_f32 v[152:153], v[144:145], v[238:239], v[152:153]
	v_pk_mul_f32 v[146:147], v[142:143], v[192:193]
	v_add_f32_dpp v154, v154, v154 quad_perm:[1,0,3,2] row_mask:0xf bank_mask:0xf bound_ctrl:1
	v_pk_mul_f32 v[148:149], v[144:145], v[200:201]
	v_add_f32_e32 v167, v152, v153
	v_add_f32_dpp v154, v154, v154 quad_perm:[2,3,0,1] row_mask:0xf bank_mask:0xf bound_ctrl:1
	v_pk_fma_f32 v[146:147], v[240:241], v[196:197], v[146:147] op_sel:[0,0,0] op_sel_hi:[0,1,1]
	v_pk_fma_f32 v[148:149], v[240:241], v[204:205], v[148:149] op_sel:[0,0,0] op_sel_hi:[0,1,1]
	v_add_f32_dpp v154, v154, v154 row_half_mirror row_mask:0xf bank_mask:0xf bound_ctrl:1
	ds_read_b128 v[126:129], v184 offset:4608
	ds_read_b128 v[130:133], v184 offset:4624
	v_add_f32_dpp v154, v154, v154 row_mirror row_mask:0xf bank_mask:0xf bound_ctrl:1
	ds_read_b64 v[236:237], v184 offset:4640
	ds_read_b128 v[134:137], v185 offset:4608
	v_pk_fma_f32 v[146:147], v[154:155], v[194:195], v[146:147] op_sel_hi:[0,1,1]
	v_pk_fma_f32 v[148:149], v[154:155], v[202:203], v[148:149] op_sel_hi:[0,1,1]
	ds_read_b128 v[222:225], v185 offset:4624
	ds_read_b64 v[238:239], v185 offset:4640
	ds_read_b32 v242, v186 offset:2944
	s_waitcnt lgkmcnt(7)
	v_pk_mul_f32 v[150:151], v[146:147], v[206:207]
	v_pk_fma_f32 v[150:151], v[148:149], v[214:215], v[150:151]
	v_pk_mul_f32 v[152:153], v[146:147], v[228:229]
	v_add_f32_e32 v154, v150, v151
	v_pk_fma_f32 v[152:153], v[148:149], v[230:231], v[152:153]
	v_pk_mul_f32 v[142:143], v[146:147], v[208:209]
	v_add_f32_dpp v154, v154, v154 quad_perm:[1,0,3,2] row_mask:0xf bank_mask:0xf bound_ctrl:1
	v_pk_mul_f32 v[144:145], v[148:149], v[216:217]
	v_add_f32_e32 v168, v152, v153
	v_add_f32_dpp v154, v154, v154 quad_perm:[2,3,0,1] row_mask:0xf bank_mask:0xf bound_ctrl:1
	v_pk_fma_f32 v[142:143], v[240:241], v[212:213], v[142:143] op_sel:[1,0,0] op_sel_hi:[1,1,1]
	v_pk_fma_f32 v[144:145], v[240:241], v[220:221], v[144:145] op_sel:[1,0,0] op_sel_hi:[1,1,1]
	v_add_f32_dpp v154, v154, v154 row_half_mirror row_mask:0xf bank_mask:0xf bound_ctrl:1
	ds_read_b128 v[190:193], v184 offset:6144
	ds_read_b128 v[194:197], v184 offset:6160
	v_add_f32_dpp v154, v154, v154 row_mirror row_mask:0xf bank_mask:0xf bound_ctrl:1
	ds_read_b64 v[228:229], v184 offset:6176
	ds_read_b128 v[198:201], v185 offset:6144
	v_pk_fma_f32 v[142:143], v[154:155], v[210:211], v[142:143] op_sel_hi:[0,1,1]
	v_pk_fma_f32 v[144:145], v[154:155], v[218:219], v[144:145] op_sel_hi:[0,1,1]
	ds_read_b128 v[202:205], v185 offset:6160
	ds_read_b64 v[230:231], v185 offset:6176
	ds_read_b32 v240, v186 offset:3008
	s_waitcnt lgkmcnt(7)
	v_pk_mul_f32 v[150:151], v[142:143], v[126:127]
	v_pk_fma_f32 v[150:151], v[144:145], v[134:135], v[150:151]
	v_pk_mul_f32 v[152:153], v[142:143], v[232:233]
	v_add_f32_e32 v154, v150, v151
	v_pk_fma_f32 v[152:153], v[144:145], v[234:235], v[152:153]
	v_pk_mul_f32 v[146:147], v[142:143], v[128:129]
	v_add_f32_dpp v154, v154, v154 quad_perm:[1,0,3,2] row_mask:0xf bank_mask:0xf bound_ctrl:1
	v_pk_mul_f32 v[148:149], v[144:145], v[136:137]
	v_add_f32_e32 v169, v152, v153
	v_add_f32_dpp v154, v154, v154 quad_perm:[2,3,0,1] row_mask:0xf bank_mask:0xf bound_ctrl:1
	v_pk_fma_f32 v[146:147], v[242:243], v[132:133], v[146:147] op_sel:[0,0,0] op_sel_hi:[0,1,1]
	v_pk_fma_f32 v[148:149], v[242:243], v[224:225], v[148:149] op_sel:[0,0,0] op_sel_hi:[0,1,1]
	v_add_f32_dpp v154, v154, v154 row_half_mirror row_mask:0xf bank_mask:0xf bound_ctrl:1
	ds_read_b128 v[206:209], v184 offset:7680
	ds_read_b128 v[210:213], v184 offset:7696
	v_add_f32_dpp v154, v154, v154 row_mirror row_mask:0xf bank_mask:0xf bound_ctrl:1
	ds_read_b64 v[232:233], v184 offset:7712
	ds_read_b128 v[214:217], v185 offset:7680
	v_pk_fma_f32 v[146:147], v[154:155], v[130:131], v[146:147] op_sel_hi:[0,1,1]
	v_pk_fma_f32 v[148:149], v[154:155], v[222:223], v[148:149] op_sel_hi:[0,1,1]
	ds_read_b128 v[218:221], v185 offset:7696
	ds_read_b64 v[234:235], v185 offset:7712
	ds_read_b32 v241, v186 offset:3072
	s_waitcnt lgkmcnt(7)
	v_pk_mul_f32 v[150:151], v[146:147], v[190:191]
	v_pk_fma_f32 v[150:151], v[148:149], v[198:199], v[150:151]
	v_pk_mul_f32 v[152:153], v[146:147], v[236:237]
	v_add_f32_e32 v154, v150, v151
	v_pk_fma_f32 v[152:153], v[148:149], v[238:239], v[152:153]
	v_pk_mul_f32 v[142:143], v[146:147], v[192:193]
	v_add_f32_dpp v154, v154, v154 quad_perm:[1,0,3,2] row_mask:0xf bank_mask:0xf bound_ctrl:1
	v_pk_mul_f32 v[144:145], v[148:149], v[200:201]
	v_add_f32_e32 v170, v152, v153
	v_add_f32_dpp v154, v154, v154 quad_perm:[2,3,0,1] row_mask:0xf bank_mask:0xf bound_ctrl:1
	v_pk_fma_f32 v[142:143], v[240:241], v[196:197], v[142:143] op_sel:[0,0,0] op_sel_hi:[0,1,1]
	v_pk_fma_f32 v[144:145], v[240:241], v[204:205], v[144:145] op_sel:[0,0,0] op_sel_hi:[0,1,1]
	v_add_f32_dpp v154, v154, v154 row_half_mirror row_mask:0xf bank_mask:0xf bound_ctrl:1
	ds_read_b128 v[126:129], v184 offset:9216
	ds_read_b128 v[130:133], v184 offset:9232
	v_add_f32_dpp v154, v154, v154 row_mirror row_mask:0xf bank_mask:0xf bound_ctrl:1
	ds_read_b64 v[236:237], v184 offset:9248
	ds_read_b128 v[134:137], v185 offset:9216
	v_pk_fma_f32 v[142:143], v[154:155], v[194:195], v[142:143] op_sel_hi:[0,1,1]
	v_pk_fma_f32 v[144:145], v[154:155], v[202:203], v[144:145] op_sel_hi:[0,1,1]
	ds_read_b128 v[222:225], v185 offset:9232
	ds_read_b64 v[238:239], v185 offset:9248
	ds_read_b32 v242, v186 offset:3136
	s_waitcnt lgkmcnt(7)
; __device__ __forceinline__ void wkv_phase(const WkvT& W, unsigned char* lds) {
;     ...
;                 const float* pp = sP + bo + jj * 12;
;                 const float* pv = sV + bi * 512 + il;
;                 f32x4 nA = *(const f32x4*)pp, nB = *(const f32x4*)(pp + 4); f32x2 nr = *(const f32x2*)(pp + 8); float nv = pv[0];
;                 float yk0 = 0.f, yk1 = 0.f, ep = 0.f;
;                 const bool oddrow = (lane & 16) != 0;
; #pragma unroll
;                 for (int t = 0; t < 32; ++t) {
;                     const f32x2 a2 = {nA[0], nA[1]}, w2 = {nA[2], nA[3]}, b2 = {nB[0], nB[1]}, k2 = {nB[2], nB[3]}, r2 = nr; const float v = nv;
;                     if (t + 1 < 32) { nA = *(const f32x4*)(pp + (t + 1) * 384); nB = *(const f32x4*)(pp + (t + 1) * 384 + 4); nr = *(const f32x2*)(pp + (t + 1) * 384 + 8); nv = pv[(t + 1) * 16]; }
;                     float S0 = S.x, S1 = S.y;
;                     float d = S0 * a2.x; d = __builtin_fmaf(S1, a2.y, d);
;                     float t0 = S0 * w2.x; t0 = __builtin_fmaf(v, k2.x, t0); asm volatile("" : "+v"(t0));
;                     float t1 = S1 * w2.y; t1 = __builtin_fmaf(v, k2.y, t1); asm volatile("" : "+v"(t1));
;                     float yprev; const float sa = wkv_reduce(d, ep, yprev);
;                     S0 = __builtin_fmaf(sa, b2.x, t0); asm volatile("" : "+v"(S0));
;                     S1 = __builtin_fmaf(sa, b2.y, t1); asm volatile("" : "+v"(S1));
;                     ep = S0 * r2.x; ep = __builtin_fmaf(S1, r2.y, ep);
;                     S.x = S0; S.y = S1;
;                     if (t >= 1) { const bool hit = oddrow && ((lane & 15) == ((t - 1) & 15)); if (t <= 16) yk0 = hit ? yprev : yk0; else yk1 = hit ? yprev : yk1; }
;                 }
;                 { float ylast; (void)wkv_reduce(0.f, ep, ylast); yk1 = (oddrow && (lane & 15) == 15) ? ylast : yk1; }
;                 if (oddrow) { sY[bi * 512 + (lane & 15) * 16 + il] = yk0; sY[bi * 512 + (16 + (lane & 15)) * 16 + il] = yk1; }
	v_pk_mul_f32 v[150:151], v[142:143], v[206:207]
	v_pk_fma_f32 v[150:151], v[144:145], v[214:215], v[150:151]
	v_pk_mul_f32 v[152:153], v[142:143], v[228:229]
	v_add_f32_e32 v154, v150, v151
	v_pk_fma_f32 v[152:153], v[144:145], v[230:231], v[152:153]
	v_pk_mul_f32 v[146:147], v[142:143], v[208:209]
	v_add_f32_dpp v154, v154, v154 quad_perm:[1,0,3,2] row_mask:0xf bank_mask:0xf bound_ctrl:1
	v_pk_mul_f32 v[148:149], v[144:145], v[216:217]
	v_add_f32_e32 v171, v152, v153
	v_add_f32_dpp v154, v154, v154 quad_perm:[2,3,0,1] row_mask:0xf bank_mask:0xf bound_ctrl:1
	v_pk_fma_f32 v[146:147], v[240:241], v[212:213], v[146:147] op_sel:[1,0,0] op_sel_hi:[1,1,1]
	v_pk_fma_f32 v[148:149], v[240:241], v[220:221], v[148:149] op_sel:[1,0,0] op_sel_hi:[1,1,1]
	v_add_f32_dpp v154, v154, v154 row_half_mirror row_mask:0xf bank_mask:0xf bound_ctrl:1
	ds_read_b128 v[190:193], v184 offset:10752
	ds_read_b128 v[194:197], v184 offset:10768
	v_add_f32_dpp v154, v154, v154 row_mirror row_mask:0xf bank_mask:0xf bound_ctrl:1
	ds_read_b64 v[228:229], v184 offset:10784
	ds_read_b128 v[198:201], v185 offset:10752
	v_pk_fma_f32 v[146:147], v[154:155], v[210:211], v[146:147] op_sel_hi:[0,1,1]
	v_pk_fma_f32 v[148:149], v[154:155], v[218:219], v[148:149] op_sel_hi:[0,1,1]
	ds_read_b128 v[202:205], v185 offset:10768
	ds_read_b64 v[230:231], v185 offset:10784
	ds_read_b32 v240, v186 offset:3200
	s_waitcnt lgkmcnt(7)
	v_add_f32_dpp v172, v156, v156 row_ror:8 row_mask:0xf bank_mask:0x3
	v_add_f32_dpp v172, v164, v164 row_ror:8 row_mask:0xf bank_mask:0xc
	v_add_f32_dpp v173, v157, v157 row_ror:8 row_mask:0xf bank_mask:0x3
	v_add_f32_dpp v173, v165, v165 row_ror:8 row_mask:0xf bank_mask:0xc
	v_add_f32_dpp v174, v158, v158 row_ror:8 row_mask:0xf bank_mask:0x3
	v_add_f32_dpp v174, v166, v166 row_ror:8 row_mask:0xf bank_mask:0xc
	v_add_f32_dpp v175, v159, v159 row_ror:8 row_mask:0xf bank_mask:0x3
	v_add_f32_dpp v175, v167, v167 row_ror:8 row_mask:0xf bank_mask:0xc
	v_add_f32_dpp v176, v160, v160 row_ror:8 row_mask:0xf bank_mask:0x3
	v_add_f32_dpp v176, v168, v168 row_ror:8 row_mask:0xf bank_mask:0xc
	v_add_f32_dpp v177, v161, v161 row_ror:8 row_mask:0xf bank_mask:0x3
	v_add_f32_dpp v177, v169, v169 row_ror:8 row_mask:0xf bank_mask:0xc
	v_add_f32_dpp v178, v162, v162 row_ror:8 row_mask:0xf bank_mask:0x3
	v_add_f32_dpp v178, v170, v170 row_ror:8 row_mask:0xf bank_mask:0xc
	v_add_f32_dpp v179, v163, v163 row_ror:8 row_mask:0xf bank_mask:0x3
	v_add_f32_dpp v179, v171, v171 row_ror:8 row_mask:0xf bank_mask:0xc
	v_add_f32_dpp v156, v172, v172 row_half_mirror row_mask:0xf bank_mask:0x5
	v_add_f32_dpp v156, v176, v176 row_half_mirror row_mask:0xf bank_mask:0xa
	v_add_f32_dpp v157, v173, v173 row_half_mirror row_mask:0xf bank_mask:0x5
	v_add_f32_dpp v157, v177, v177 row_half_mirror row_mask:0xf bank_mask:0xa
	v_add_f32_dpp v158, v174, v174 row_half_mirror row_mask:0xf bank_mask:0x5
	v_add_f32_dpp v158, v178, v178 row_half_mirror row_mask:0xf bank_mask:0xa
	v_add_f32_dpp v159, v175, v175 row_half_mirror row_mask:0xf bank_mask:0x5
	v_add_f32_dpp v159, v179, v179 row_half_mirror row_mask:0xf bank_mask:0xa
	v_cndmask_b32_e64 v176, v158, v156, s[14:15]
	v_cndmask_b32_e64 v177, v159, v157, s[14:15]
	v_cndmask_b32_e64 v178, v156, v158, s[14:15]
	v_cndmask_b32_e64 v179, v157, v159, s[14:15]
	v_add_f32_dpp v172, v176, v178 quad_perm:[2,3,0,1] row_mask:0xf bank_mask:0xf
	v_add_f32_dpp v173, v177, v179 quad_perm:[2,3,0,1] row_mask:0xf bank_mask:0xf
	v_cndmask_b32_e64 v176, v173, v172, s[16:17]
	v_cndmask_b32_e64 v178, v172, v173, s[16:17]
	s_nop 0
	v_add_f32_dpp v180, v176, v178 quad_perm:[1,0,3,2] row_mask:0xf bank_mask:0xf
	v_pk_mul_f32 v[150:151], v[146:147], v[126:127]
	v_pk_fma_f32 v[150:151], v[148:149], v[134:135], v[150:151]
	v_pk_mul_f32 v[152:153], v[146:147], v[232:233]
	v_add_f32_e32 v154, v150, v151
	v_pk_fma_f32 v[152:153], v[148:149], v[234:235], v[152:153]
	v_pk_mul_f32 v[142:143], v[146:147], v[128:129]
	v_add_f32_dpp v154, v154, v154 quad_perm:[1,0,3,2] row_mask:0xf bank_mask:0xf bound_ctrl:1
	v_pk_mul_f32 v[144:145], v[148:149], v[136:137]
	v_add_f32_e32 v156, v152, v153
	v_add_f32_dpp v154, v154, v154 quad_perm:[2,3,0,1] row_mask:0xf bank_mask:0xf bound_ctrl:1
	v_pk_fma_f32 v[142:143], v[242:243], v[132:133], v[142:143] op_sel:[0,0,0] op_sel_hi:[0,1,1]
	v_pk_fma_f32 v[144:145], v[242:243], v[224:225], v[144:145] op_sel:[0,0,0] op_sel_hi:[0,1,1]
	v_add_f32_dpp v154, v154, v154 row_half_mirror row_mask:0xf bank_mask:0xf bound_ctrl:1
	ds_read_b128 v[206:209], v184 offset:12288
	ds_read_b128 v[210:213], v184 offset:12304
	v_add_f32_dpp v154, v154, v154 row_mirror row_mask:0xf bank_mask:0xf bound_ctrl:1
	ds_read_b64 v[232:233], v184 offset:12320
	ds_read_b128 v[214:217], v185 offset:12288
	v_pk_fma_f32 v[142:143], v[154:155], v[130:131], v[142:143] op_sel_hi:[0,1,1]
	v_pk_fma_f32 v[144:145], v[154:155], v[222:223], v[144:145] op_sel_hi:[0,1,1]
	ds_read_b128 v[218:221], v185 offset:12304
	ds_read_b64 v[234:235], v185 offset:12320
	ds_read_b32 v241, v186 offset:3264
	s_waitcnt lgkmcnt(7)
; __device__ __forceinline__ void wkv_phase(const WkvT& W, unsigned char* lds) {
;     ...
;                 const float* pp = sP + bo + jj * 12;
;                 const float* pv = sV + bi * 512 + il;
;                 f32x4 nA = *(const f32x4*)pp, nB = *(const f32x4*)(pp + 4); f32x2 nr = *(const f32x2*)(pp + 8); float nv = pv[0];
;                 float yk0 = 0.f, yk1 = 0.f, ep = 0.f;
;                 const bool oddrow = (lane & 16) != 0;
; #pragma unroll
;                 for (int t = 0; t < 32; ++t) {
;                     const f32x2 a2 = {nA[0], nA[1]}, w2 = {nA[2], nA[3]}, b2 = {nB[0], nB[1]}, k2 = {nB[2], nB[3]}, r2 = nr; const float v = nv;
;                     if (t + 1 < 32) { nA = *(const f32x4*)(pp + (t + 1) * 384); nB = *(const f32x4*)(pp + (t + 1) * 384 + 4); nr = *(const f32x2*)(pp + (t + 1) * 384 + 8); nv = pv[(t + 1) * 16]; }
;                     float S0 = S.x, S1 = S.y;
;                     float d = S0 * a2.x; d = __builtin_fmaf(S1, a2.y, d);
;                     float t0 = S0 * w2.x; t0 = __builtin_fmaf(v, k2.x, t0); asm volatile("" : "+v"(t0));
;                     float t1 = S1 * w2.y; t1 = __builtin_fmaf(v, k2.y, t1); asm volatile("" : "+v"(t1));
;                     float yprev; const float sa = wkv_reduce(d, ep, yprev);
;                     S0 = __builtin_fmaf(sa, b2.x, t0); asm volatile("" : "+v"(S0));
;                     S1 = __builtin_fmaf(sa, b2.y, t1); asm volatile("" : "+v"(S1));
;                     ep = S0 * r2.x; ep = __builtin_fmaf(S1, r2.y, ep);
;                     S.x = S0; S.y = S1;
;                     if (t >= 1) { const bool hit = oddrow && ((lane & 15) == ((t - 1) & 15)); if (t <= 16) yk0 = hit ? yprev : yk0; else yk1 = hit ? yprev : yk1; }
;                 }
	v_pk_mul_f32 v[150:151], v[142:143], v[190:191]
	v_pk_fma_f32 v[150:151], v[144:145], v[198:199], v[150:151]
	v_pk_mul_f32 v[152:153], v[142:143], v[236:237]
	v_add_f32_e32 v154, v150, v151
	v_pk_fma_f32 v[152:153], v[144:145], v[238:239], v[152:153]
	v_pk_mul_f32 v[146:147], v[142:143], v[192:193]
	v_add_f32_dpp v154, v154, v154 quad_perm:[1,0,3,2] row_mask:0xf bank_mask:0xf bound_ctrl:1
	v_pk_mul_f32 v[148:149], v[144:145], v[200:201]
	v_add_f32_e32 v157, v152, v153
	v_add_f32_dpp v154, v154, v154 quad_perm:[2,3,0,1] row_mask:0xf bank_mask:0xf bound_ctrl:1
	v_pk_fma_f32 v[146:147], v[240:241], v[196:197], v[146:147] op_sel:[0,0,0] op_sel_hi:[0,1,1]
	v_pk_fma_f32 v[148:149], v[240:241], v[204:205], v[148:149] op_sel:[0,0,0] op_sel_hi:[0,1,1]
	v_add_f32_dpp v154, v154, v154 row_half_mirror row_mask:0xf bank_mask:0xf bound_ctrl:1
	ds_read_b128 v[126:129], v184 offset:13824
	ds_read_b128 v[130:133], v184 offset:13840
	v_add_f32_dpp v154, v154, v154 row_mirror row_mask:0xf bank_mask:0xf bound_ctrl:1
	ds_read_b64 v[236:237], v184 offset:13856
	ds_read_b128 v[134:137], v185 offset:13824
	v_pk_fma_f32 v[146:147], v[154:155], v[194:195], v[146:147] op_sel_hi:[0,1,1]
	v_pk_fma_f32 v[148:149], v[154:155], v[202:203], v[148:149] op_sel_hi:[0,1,1]
	ds_read_b128 v[222:225], v185 offset:13840
	ds_read_b64 v[238:239], v185 offset:13856
	ds_read_b32 v242, v186 offset:3328
	s_waitcnt lgkmcnt(7)
	v_pk_mul_f32 v[150:151], v[146:147], v[206:207]
	v_pk_fma_f32 v[150:151], v[148:149], v[214:215], v[150:151]
	v_pk_mul_f32 v[152:153], v[146:147], v[228:229]
	v_add_f32_e32 v154, v150, v151
	v_pk_fma_f32 v[152:153], v[148:149], v[230:231], v[152:153]
	v_pk_mul_f32 v[142:143], v[146:147], v[208:209]
	v_add_f32_dpp v154, v154, v154 quad_perm:[1,0,3,2] row_mask:0xf bank_mask:0xf bound_ctrl:1
	v_pk_mul_f32 v[144:145], v[148:149], v[216:217]
	v_add_f32_e32 v158, v152, v153
	v_add_f32_dpp v154, v154, v154 quad_perm:[2,3,0,1] row_mask:0xf bank_mask:0xf bound_ctrl:1
	v_pk_fma_f32 v[142:143], v[240:241], v[212:213], v[142:143] op_sel:[1,0,0] op_sel_hi:[1,1,1]
	v_pk_fma_f32 v[144:145], v[240:241], v[220:221], v[144:145] op_sel:[1,0,0] op_sel_hi:[1,1,1]
	v_add_f32_dpp v154, v154, v154 row_half_mirror row_mask:0xf bank_mask:0xf bound_ctrl:1
	ds_read_b128 v[190:193], v184 offset:15360
	ds_read_b128 v[194:197], v184 offset:15376
	v_add_f32_dpp v154, v154, v154 row_mirror row_mask:0xf bank_mask:0xf bound_ctrl:1
	ds_read_b64 v[228:229], v184 offset:15392
	ds_read_b128 v[198:201], v185 offset:15360
	v_pk_fma_f32 v[142:143], v[154:155], v[210:211], v[142:143] op_sel_hi:[0,1,1]
	v_pk_fma_f32 v[144:145], v[154:155], v[218:219], v[144:145] op_sel_hi:[0,1,1]
	ds_read_b128 v[202:205], v185 offset:15376
	ds_read_b64 v[230:231], v185 offset:15392
	ds_read_b32 v240, v186 offset:3392
	s_waitcnt lgkmcnt(7)
	v_pk_mul_f32 v[150:151], v[142:143], v[126:127]
	v_pk_fma_f32 v[150:151], v[144:145], v[134:135], v[150:151]
	v_pk_mul_f32 v[152:153], v[142:143], v[232:233]
	v_add_f32_e32 v154, v150, v151
	v_pk_fma_f32 v[152:153], v[144:145], v[234:235], v[152:153]
	v_pk_mul_f32 v[146:147], v[142:143], v[128:129]
	v_add_f32_dpp v154, v154, v154 quad_perm:[1,0,3,2] row_mask:0xf bank_mask:0xf bound_ctrl:1
	v_pk_mul_f32 v[148:149], v[144:145], v[136:137]
	v_add_f32_e32 v159, v152, v153
	v_add_f32_dpp v154, v154, v154 quad_perm:[2,3,0,1] row_mask:0xf bank_mask:0xf bound_ctrl:1
	v_pk_fma_f32 v[146:147], v[242:243], v[132:133], v[146:147] op_sel:[0,0,0] op_sel_hi:[0,1,1]
	v_pk_fma_f32 v[148:149], v[242:243], v[224:225], v[148:149] op_sel:[0,0,0] op_sel_hi:[0,1,1]
	v_add_f32_dpp v154, v154, v154 row_half_mirror row_mask:0xf bank_mask:0xf bound_ctrl:1
	ds_read_b128 v[206:209], v184 offset:16896
	ds_read_b128 v[210:213], v184 offset:16912
	v_add_f32_dpp v154, v154, v154 row_mirror row_mask:0xf bank_mask:0xf bound_ctrl:1
	ds_read_b64 v[232:233], v184 offset:16928
	ds_read_b128 v[214:217], v185 offset:16896
	v_pk_fma_f32 v[146:147], v[154:155], v[130:131], v[146:147] op_sel_hi:[0,1,1]
	v_pk_fma_f32 v[148:149], v[154:155], v[222:223], v[148:149] op_sel_hi:[0,1,1]
	ds_read_b128 v[218:221], v185 offset:16912
	ds_read_b64 v[234:235], v185 offset:16928
	ds_read_b32 v241, v186 offset:3456
	s_waitcnt lgkmcnt(7)
	v_pk_mul_f32 v[150:151], v[146:147], v[190:191]
	v_pk_fma_f32 v[150:151], v[148:149], v[198:199], v[150:151]
	v_pk_mul_f32 v[152:153], v[146:147], v[236:237]
	v_add_f32_e32 v154, v150, v151
	v_pk_fma_f32 v[152:153], v[148:149], v[238:239], v[152:153]
	v_pk_mul_f32 v[142:143], v[146:147], v[192:193]
	v_add_f32_dpp v154, v154, v154 quad_perm:[1,0,3,2] row_mask:0xf bank_mask:0xf bound_ctrl:1
	v_pk_mul_f32 v[144:145], v[148:149], v[200:201]
	v_add_f32_e32 v160, v152, v153
	v_add_f32_dpp v154, v154, v154 quad_perm:[2,3,0,1] row_mask:0xf bank_mask:0xf bound_ctrl:1
	v_pk_fma_f32 v[142:143], v[240:241], v[196:197], v[142:143] op_sel:[0,0,0] op_sel_hi:[0,1,1]
	v_pk_fma_f32 v[144:145], v[240:241], v[204:205], v[144:145] op_sel:[0,0,0] op_sel_hi:[0,1,1]
	v_add_f32_dpp v154, v154, v154 row_half_mirror row_mask:0xf bank_mask:0xf bound_ctrl:1
	ds_read_b128 v[126:129], v184 offset:18432
	ds_read_b128 v[130:133], v184 offset:18448
	v_add_f32_dpp v154, v154, v154 row_mirror row_mask:0xf bank_mask:0xf bound_ctrl:1
	ds_read_b64 v[236:237], v184 offset:18464
	ds_read_b128 v[134:137], v185 offset:18432
	v_pk_fma_f32 v[142:143], v[154:155], v[194:195], v[142:143] op_sel_hi:[0,1,1]
	v_pk_fma_f32 v[144:145], v[154:155], v[202:203], v[144:145] op_sel_hi:[0,1,1]
	ds_read_b128 v[222:225], v185 offset:18448
	ds_read_b64 v[238:239], v185 offset:18464
	ds_read_b32 v242, v186 offset:3520
	s_waitcnt lgkmcnt(7)
; __device__ __forceinline__ void wkv_phase(const WkvT& W, unsigned char* lds) {
;     ...
;                 const float* pp = sP + bo + jj * 12;
;                 const float* pv = sV + bi * 512 + il;
;                 f32x4 nA = *(const f32x4*)pp, nB = *(const f32x4*)(pp + 4); f32x2 nr = *(const f32x2*)(pp + 8); float nv = pv[0];
;                 float yk0 = 0.f, yk1 = 0.f, ep = 0.f;
;                 const bool oddrow = (lane & 16) != 0;
; #pragma unroll
;                 for (int t = 0; t < 32; ++t) {
;                     const f32x2 a2 = {nA[0], nA[1]}, w2 = {nA[2], nA[3]}, b2 = {nB[0], nB[1]}, k2 = {nB[2], nB[3]}, r2 = nr; const float v = nv;
;                     if (t + 1 < 32) { nA = *(const f32x4*)(pp + (t + 1) * 384); nB = *(const f32x4*)(pp + (t + 1) * 384 + 4); nr = *(const f32x2*)(pp + (t + 1) * 384 + 8); nv = pv[(t + 1) * 16]; }
;                     float S0 = S.x, S1 = S.y;
;                     float d = S0 * a2.x; d = __builtin_fmaf(S1, a2.y, d);
;                     float t0 = S0 * w2.x; t0 = __builtin_fmaf(v, k2.x, t0); asm volatile("" : "+v"(t0));
;                     float t1 = S1 * w2.y; t1 = __builtin_fmaf(v, k2.y, t1); asm volatile("" : "+v"(t1));
;                     float yprev; const float sa = wkv_reduce(d, ep, yprev);
;                     S0 = __builtin_fmaf(sa, b2.x, t0); asm volatile("" : "+v"(S0));
;                     S1 = __builtin_fmaf(sa, b2.y, t1); asm volatile("" : "+v"(S1));
;                     ep = S0 * r2.x; ep = __builtin_fmaf(S1, r2.y, ep);
;                     S.x = S0; S.y = S1;
;                     if (t >= 1) { const bool hit = oddrow && ((lane & 15) == ((t - 1) & 15)); if (t <= 16) yk0 = hit ? yprev : yk0; else yk1 = hit ? yprev : yk1; }
;                 }
	v_pk_mul_f32 v[150:151], v[142:143], v[206:207]
	v_pk_fma_f32 v[150:151], v[144:145], v[214:215], v[150:151]
	v_pk_mul_f32 v[152:153], v[142:143], v[228:229]
	v_add_f32_e32 v154, v150, v151
	v_pk_fma_f32 v[152:153], v[144:145], v[230:231], v[152:153]
	v_pk_mul_f32 v[146:147], v[142:143], v[208:209]
	v_add_f32_dpp v154, v154, v154 quad_perm:[1,0,3,2] row_mask:0xf bank_mask:0xf bound_ctrl:1
	v_pk_mul_f32 v[148:149], v[144:145], v[216:217]
	v_add_f32_e32 v161, v152, v153
	v_add_f32_dpp v154, v154, v154 quad_perm:[2,3,0,1] row_mask:0xf bank_mask:0xf bound_ctrl:1
	v_pk_fma_f32 v[146:147], v[240:241], v[212:213], v[146:147] op_sel:[1,0,0] op_sel_hi:[1,1,1]
	v_pk_fma_f32 v[148:149], v[240:241], v[220:221], v[148:149] op_sel:[1,0,0] op_sel_hi:[1,1,1]
	v_add_f32_dpp v154, v154, v154 row_half_mirror row_mask:0xf bank_mask:0xf bound_ctrl:1
	ds_read_b128 v[190:193], v184 offset:19968
	ds_read_b128 v[194:197], v184 offset:19984
	v_add_f32_dpp v154, v154, v154 row_mirror row_mask:0xf bank_mask:0xf bound_ctrl:1
	ds_read_b64 v[228:229], v184 offset:20000
	ds_read_b128 v[198:201], v185 offset:19968
	v_pk_fma_f32 v[146:147], v[154:155], v[210:211], v[146:147] op_sel_hi:[0,1,1]
	v_pk_fma_f32 v[148:149], v[154:155], v[218:219], v[148:149] op_sel_hi:[0,1,1]
	ds_read_b128 v[202:205], v185 offset:19984
	ds_read_b64 v[230:231], v185 offset:20000
	ds_read_b32 v240, v186 offset:3584
	s_waitcnt lgkmcnt(7)
	v_pk_mul_f32 v[150:151], v[146:147], v[126:127]
	v_pk_fma_f32 v[150:151], v[148:149], v[134:135], v[150:151]
	v_pk_mul_f32 v[152:153], v[146:147], v[232:233]
	v_add_f32_e32 v154, v150, v151
	v_pk_fma_f32 v[152:153], v[148:149], v[234:235], v[152:153]
	v_pk_mul_f32 v[142:143], v[146:147], v[128:129]
	v_add_f32_dpp v154, v154, v154 quad_perm:[1,0,3,2] row_mask:0xf bank_mask:0xf bound_ctrl:1
	v_pk_mul_f32 v[144:145], v[148:149], v[136:137]
	v_add_f32_e32 v162, v152, v153
	v_add_f32_dpp v154, v154, v154 quad_perm:[2,3,0,1] row_mask:0xf bank_mask:0xf bound_ctrl:1
	v_pk_fma_f32 v[142:143], v[242:243], v[132:133], v[142:143] op_sel:[0,0,0] op_sel_hi:[0,1,1]
	v_pk_fma_f32 v[144:145], v[242:243], v[224:225], v[144:145] op_sel:[0,0,0] op_sel_hi:[0,1,1]
	v_add_f32_dpp v154, v154, v154 row_half_mirror row_mask:0xf bank_mask:0xf bound_ctrl:1
	ds_read_b128 v[206:209], v184 offset:21504
	ds_read_b128 v[210:213], v184 offset:21520
	v_add_f32_dpp v154, v154, v154 row_mirror row_mask:0xf bank_mask:0xf bound_ctrl:1
	ds_read_b64 v[232:233], v184 offset:21536
	ds_read_b128 v[214:217], v185 offset:21504
	v_pk_fma_f32 v[142:143], v[154:155], v[130:131], v[142:143] op_sel_hi:[0,1,1]
	v_pk_fma_f32 v[144:145], v[154:155], v[222:223], v[144:145] op_sel_hi:[0,1,1]
	ds_read_b128 v[218:221], v185 offset:21520
	ds_read_b64 v[234:235], v185 offset:21536
	ds_read_b32 v241, v186 offset:3648
	s_waitcnt lgkmcnt(7)
	v_pk_mul_f32 v[150:151], v[142:143], v[190:191]
	v_pk_fma_f32 v[150:151], v[144:145], v[198:199], v[150:151]
	v_pk_mul_f32 v[152:153], v[142:143], v[236:237]
	v_add_f32_e32 v154, v150, v151
	v_pk_fma_f32 v[152:153], v[144:145], v[238:239], v[152:153]
	v_pk_mul_f32 v[146:147], v[142:143], v[192:193]
	v_add_f32_dpp v154, v154, v154 quad_perm:[1,0,3,2] row_mask:0xf bank_mask:0xf bound_ctrl:1
	v_pk_mul_f32 v[148:149], v[144:145], v[200:201]
	v_add_f32_e32 v163, v152, v153
	v_add_f32_dpp v154, v154, v154 quad_perm:[2,3,0,1] row_mask:0xf bank_mask:0xf bound_ctrl:1
	v_pk_fma_f32 v[146:147], v[240:241], v[196:197], v[146:147] op_sel:[0,0,0] op_sel_hi:[0,1,1]
	v_pk_fma_f32 v[148:149], v[240:241], v[204:205], v[148:149] op_sel:[0,0,0] op_sel_hi:[0,1,1]
	v_add_f32_dpp v154, v154, v154 row_half_mirror row_mask:0xf bank_mask:0xf bound_ctrl:1
	ds_read_b128 v[126:129], v184 offset:23040
	ds_read_b128 v[130:133], v184 offset:23056
	v_add_f32_dpp v154, v154, v154 row_mirror row_mask:0xf bank_mask:0xf bound_ctrl:1
	ds_read_b64 v[236:237], v184 offset:23072
	ds_read_b128 v[134:137], v185 offset:23040
	v_pk_fma_f32 v[146:147], v[154:155], v[194:195], v[146:147] op_sel_hi:[0,1,1]
	v_pk_fma_f32 v[148:149], v[154:155], v[202:203], v[148:149] op_sel_hi:[0,1,1]
	ds_read_b128 v[222:225], v185 offset:23056
	ds_read_b64 v[238:239], v185 offset:23072
	ds_read_b32 v242, v186 offset:3712
	s_waitcnt lgkmcnt(7)
	v_pk_mul_f32 v[150:151], v[146:147], v[206:207]
	v_pk_fma_f32 v[150:151], v[148:149], v[214:215], v[150:151]
	v_pk_mul_f32 v[152:153], v[146:147], v[228:229]
	v_add_f32_e32 v154, v150, v151
	v_pk_fma_f32 v[152:153], v[148:149], v[230:231], v[152:153]
	v_pk_mul_f32 v[142:143], v[146:147], v[208:209]
	v_add_f32_dpp v154, v154, v154 quad_perm:[1,0,3,2] row_mask:0xf bank_mask:0xf bound_ctrl:1
	v_pk_mul_f32 v[144:145], v[148:149], v[216:217]
	v_add_f32_e32 v164, v152, v153
	v_add_f32_dpp v154, v154, v154 quad_perm:[2,3,0,1] row_mask:0xf bank_mask:0xf bound_ctrl:1
	v_pk_fma_f32 v[142:143], v[240:241], v[212:213], v[142:143] op_sel:[1,0,0] op_sel_hi:[1,1,1]
	v_pk_fma_f32 v[144:145], v[240:241], v[220:221], v[144:145] op_sel:[1,0,0] op_sel_hi:[1,1,1]
	v_add_f32_dpp v154, v154, v154 row_half_mirror row_mask:0xf bank_mask:0xf bound_ctrl:1
	ds_read_b128 v[190:193], v184 offset:24576
	ds_read_b128 v[194:197], v184 offset:24592
	v_add_f32_dpp v154, v154, v154 row_mirror row_mask:0xf bank_mask:0xf bound_ctrl:1
	ds_read_b64 v[228:229], v184 offset:24608
	ds_read_b128 v[198:201], v185 offset:24576
	v_pk_fma_f32 v[142:143], v[154:155], v[210:211], v[142:143] op_sel_hi:[0,1,1]
	v_pk_fma_f32 v[144:145], v[154:155], v[218:219], v[144:145] op_sel_hi:[0,1,1]
	ds_read_b128 v[202:205], v185 offset:24592
	ds_read_b64 v[230:231], v185 offset:24608
	ds_read_b32 v240, v186 offset:3776
	s_waitcnt lgkmcnt(7)
; __device__ __forceinline__ void wkv_phase(const WkvT& W, unsigned char* lds) {
;     ...
;                 const float* pp = sP + bo + jj * 12;
;                 const float* pv = sV + bi * 512 + il;
;                 f32x4 nA = *(const f32x4*)pp, nB = *(const f32x4*)(pp + 4); f32x2 nr = *(const f32x2*)(pp + 8); float nv = pv[0];
;                 float yk0 = 0.f, yk1 = 0.f, ep = 0.f;
;                 const bool oddrow = (lane & 16) != 0;
; #pragma unroll
;                 for (int t = 0; t < 32; ++t) {
;                     const f32x2 a2 = {nA[0], nA[1]}, w2 = {nA[2], nA[3]}, b2 = {nB[0], nB[1]}, k2 = {nB[2], nB[3]}, r2 = nr; const float v = nv;
;                     if (t + 1 < 32) { nA = *(const f32x4*)(pp + (t + 1) * 384); nB = *(const f32x4*)(pp + (t + 1) * 384 + 4); nr = *(const f32x2*)(pp + (t + 1) * 384 + 8); nv = pv[(t + 1) * 16]; }
;                     float S0 = S.x, S1 = S.y;
;                     float d = S0 * a2.x; d = __builtin_fmaf(S1, a2.y, d);
;                     float t0 = S0 * w2.x; t0 = __builtin_fmaf(v, k2.x, t0); asm volatile("" : "+v"(t0));
;                     float t1 = S1 * w2.y; t1 = __builtin_fmaf(v, k2.y, t1); asm volatile("" : "+v"(t1));
;                     float yprev; const float sa = wkv_reduce(d, ep, yprev);
;                     S0 = __builtin_fmaf(sa, b2.x, t0); asm volatile("" : "+v"(S0));
;                     S1 = __builtin_fmaf(sa, b2.y, t1); asm volatile("" : "+v"(S1));
;                     ep = S0 * r2.x; ep = __builtin_fmaf(S1, r2.y, ep);
;                     S.x = S0; S.y = S1;
;                     if (t >= 1) { const bool hit = oddrow && ((lane & 15) == ((t - 1) & 15)); if (t <= 16) yk0 = hit ? yprev : yk0; else yk1 = hit ? yprev : yk1; }
;                 }
	v_pk_mul_f32 v[150:151], v[142:143], v[126:127]
	v_pk_fma_f32 v[150:151], v[144:145], v[134:135], v[150:151]
	v_pk_mul_f32 v[152:153], v[142:143], v[232:233]
	v_add_f32_e32 v154, v150, v151
	v_pk_fma_f32 v[152:153], v[144:145], v[234:235], v[152:153]
	v_pk_mul_f32 v[146:147], v[142:143], v[128:129]
	v_add_f32_dpp v154, v154, v154 quad_perm:[1,0,3,2] row_mask:0xf bank_mask:0xf bound_ctrl:1
	v_pk_mul_f32 v[148:149], v[144:145], v[136:137]
	v_add_f32_e32 v165, v152, v153
	v_add_f32_dpp v154, v154, v154 quad_perm:[2,3,0,1] row_mask:0xf bank_mask:0xf bound_ctrl:1
	v_pk_fma_f32 v[146:147], v[242:243], v[132:133], v[146:147] op_sel:[0,0,0] op_sel_hi:[0,1,1]
	v_pk_fma_f32 v[148:149], v[242:243], v[224:225], v[148:149] op_sel:[0,0,0] op_sel_hi:[0,1,1]
	v_add_f32_dpp v154, v154, v154 row_half_mirror row_mask:0xf bank_mask:0xf bound_ctrl:1
	ds_read_b128 v[206:209], v184 offset:26112
	ds_read_b128 v[210:213], v184 offset:26128
	v_add_f32_dpp v154, v154, v154 row_mirror row_mask:0xf bank_mask:0xf bound_ctrl:1
	ds_read_b64 v[232:233], v184 offset:26144
	ds_read_b128 v[214:217], v185 offset:26112
	v_pk_fma_f32 v[146:147], v[154:155], v[130:131], v[146:147] op_sel_hi:[0,1,1]
	v_pk_fma_f32 v[148:149], v[154:155], v[222:223], v[148:149] op_sel_hi:[0,1,1]
	ds_read_b128 v[218:221], v185 offset:26128
	ds_read_b64 v[234:235], v185 offset:26144
	ds_read_b32 v241, v186 offset:3840
	s_waitcnt lgkmcnt(7)
	v_pk_mul_f32 v[150:151], v[146:147], v[190:191]
	v_pk_fma_f32 v[150:151], v[148:149], v[198:199], v[150:151]
	v_pk_mul_f32 v[152:153], v[146:147], v[236:237]
	v_add_f32_e32 v154, v150, v151
	v_pk_fma_f32 v[152:153], v[148:149], v[238:239], v[152:153]
	v_pk_mul_f32 v[142:143], v[146:147], v[192:193]
	v_add_f32_dpp v154, v154, v154 quad_perm:[1,0,3,2] row_mask:0xf bank_mask:0xf bound_ctrl:1
	v_pk_mul_f32 v[144:145], v[148:149], v[200:201]
	v_add_f32_e32 v166, v152, v153
	v_add_f32_dpp v154, v154, v154 quad_perm:[2,3,0,1] row_mask:0xf bank_mask:0xf bound_ctrl:1
	v_pk_fma_f32 v[142:143], v[240:241], v[196:197], v[142:143] op_sel:[0,0,0] op_sel_hi:[0,1,1]
	v_pk_fma_f32 v[144:145], v[240:241], v[204:205], v[144:145] op_sel:[0,0,0] op_sel_hi:[0,1,1]
	v_add_f32_dpp v154, v154, v154 row_half_mirror row_mask:0xf bank_mask:0xf bound_ctrl:1
	ds_read_b128 v[126:129], v184 offset:27648
	ds_read_b128 v[130:133], v184 offset:27664
	v_add_f32_dpp v154, v154, v154 row_mirror row_mask:0xf bank_mask:0xf bound_ctrl:1
	ds_read_b64 v[236:237], v184 offset:27680
	ds_read_b128 v[134:137], v185 offset:27648
	v_pk_fma_f32 v[142:143], v[154:155], v[194:195], v[142:143] op_sel_hi:[0,1,1]
	v_pk_fma_f32 v[144:145], v[154:155], v[202:203], v[144:145] op_sel_hi:[0,1,1]
	ds_read_b128 v[222:225], v185 offset:27664
	ds_read_b64 v[238:239], v185 offset:27680
	ds_read_b32 v242, v186 offset:3904
	s_waitcnt lgkmcnt(7)
	v_pk_mul_f32 v[150:151], v[142:143], v[206:207]
	v_pk_fma_f32 v[150:151], v[144:145], v[214:215], v[150:151]
	v_pk_mul_f32 v[152:153], v[142:143], v[228:229]
	v_add_f32_e32 v154, v150, v151
	v_pk_fma_f32 v[152:153], v[144:145], v[230:231], v[152:153]
	v_pk_mul_f32 v[146:147], v[142:143], v[208:209]
	v_add_f32_dpp v154, v154, v154 quad_perm:[1,0,3,2] row_mask:0xf bank_mask:0xf bound_ctrl:1
	v_pk_mul_f32 v[148:149], v[144:145], v[216:217]
	v_add_f32_e32 v167, v152, v153
	v_add_f32_dpp v154, v154, v154 quad_perm:[2,3,0,1] row_mask:0xf bank_mask:0xf bound_ctrl:1
	v_pk_fma_f32 v[146:147], v[240:241], v[212:213], v[146:147] op_sel:[1,0,0] op_sel_hi:[1,1,1]
	v_pk_fma_f32 v[148:149], v[240:241], v[220:221], v[148:149] op_sel:[1,0,0] op_sel_hi:[1,1,1]
	v_add_f32_dpp v154, v154, v154 row_half_mirror row_mask:0xf bank_mask:0xf bound_ctrl:1
	ds_read_b128 v[190:193], v184 offset:29184
	ds_read_b128 v[194:197], v184 offset:29200
	v_add_f32_dpp v154, v154, v154 row_mirror row_mask:0xf bank_mask:0xf bound_ctrl:1
	ds_read_b64 v[228:229], v184 offset:29216
	ds_read_b128 v[198:201], v185 offset:29184
	v_pk_fma_f32 v[146:147], v[154:155], v[210:211], v[146:147] op_sel_hi:[0,1,1]
	v_pk_fma_f32 v[148:149], v[154:155], v[218:219], v[148:149] op_sel_hi:[0,1,1]
	ds_read_b128 v[202:205], v185 offset:29200
	ds_read_b64 v[230:231], v185 offset:29216
	ds_read_b32 v240, v186 offset:3968
	s_waitcnt lgkmcnt(7)
	v_pk_mul_f32 v[150:151], v[146:147], v[126:127]
	v_pk_fma_f32 v[150:151], v[148:149], v[134:135], v[150:151]
	v_pk_mul_f32 v[152:153], v[146:147], v[232:233]
	v_add_f32_e32 v154, v150, v151
	v_pk_fma_f32 v[152:153], v[148:149], v[234:235], v[152:153]
	v_pk_mul_f32 v[142:143], v[146:147], v[128:129]
	v_add_f32_dpp v154, v154, v154 quad_perm:[1,0,3,2] row_mask:0xf bank_mask:0xf bound_ctrl:1
	v_pk_mul_f32 v[144:145], v[148:149], v[136:137]
	v_add_f32_e32 v168, v152, v153
	v_add_f32_dpp v154, v154, v154 quad_perm:[2,3,0,1] row_mask:0xf bank_mask:0xf bound_ctrl:1
	v_pk_fma_f32 v[142:143], v[242:243], v[132:133], v[142:143] op_sel:[0,0,0] op_sel_hi:[0,1,1]
	v_pk_fma_f32 v[144:145], v[242:243], v[224:225], v[144:145] op_sel:[0,0,0] op_sel_hi:[0,1,1]
	v_add_f32_dpp v154, v154, v154 row_half_mirror row_mask:0xf bank_mask:0xf bound_ctrl:1
	ds_read_b128 v[206:209], v184 offset:30720
	ds_read_b128 v[210:213], v184 offset:30736
	v_add_f32_dpp v154, v154, v154 row_mirror row_mask:0xf bank_mask:0xf bound_ctrl:1
	ds_read_b64 v[232:233], v184 offset:30752
	ds_read_b128 v[214:217], v185 offset:30720
	v_pk_fma_f32 v[142:143], v[154:155], v[130:131], v[142:143] op_sel_hi:[0,1,1]
	v_pk_fma_f32 v[144:145], v[154:155], v[222:223], v[144:145] op_sel_hi:[0,1,1]
	ds_read_b128 v[218:221], v185 offset:30736
	ds_read_b64 v[234:235], v185 offset:30752
	ds_read_b32 v241, v186 offset:4032
	s_waitcnt lgkmcnt(7)
; __device__ __forceinline__ void wkv_phase(const WkvT& W, unsigned char* lds) {
;     ...
;                 for (int t = 0; t < 32; ++t) {
;                     const f32x2 a2 = {nA[0], nA[1]}, w2 = {nA[2], nA[3]}, b2 = {nB[0], nB[1]}, k2 = {nB[2], nB[3]}, r2 = nr; const float v = nv;
;                     if (t + 1 < 32) { nA = *(const f32x4*)(pp + (t + 1) * 384); nB = *(const f32x4*)(pp + (t + 1) * 384 + 4); nr = *(const f32x2*)(pp + (t + 1) * 384 + 8); nv = pv[(t + 1) * 16]; }
;                     float S0 = S.x, S1 = S.y;
;                     float d = S0 * a2.x; d = __builtin_fmaf(S1, a2.y, d);
;                     float t0 = S0 * w2.x; t0 = __builtin_fmaf(v, k2.x, t0); asm volatile("" : "+v"(t0));
;                     float t1 = S1 * w2.y; t1 = __builtin_fmaf(v, k2.y, t1); asm volatile("" : "+v"(t1));
;                     float yprev; const float sa = wkv_reduce(d, ep, yprev);
;                     S0 = __builtin_fmaf(sa, b2.x, t0); asm volatile("" : "+v"(S0));
;                     S1 = __builtin_fmaf(sa, b2.y, t1); asm volatile("" : "+v"(S1));
;                     ep = S0 * r2.x; ep = __builtin_fmaf(S1, r2.y, ep);
;                     S.x = S0; S.y = S1;
;                     if (t >= 1) { const bool hit = oddrow && ((lane & 15) == ((t - 1) & 15)); if (t <= 16) yk0 = hit ? yprev : yk0; else yk1 = hit ? yprev : yk1; }
;                 }
;                 { float ylast; (void)wkv_reduce(0.f, ep, ylast); yk1 = (oddrow && (lane & 15) == 15) ? ylast : yk1; }
;                 if (oddrow) { sY[bi * 512 + (lane & 15) * 16 + il] = yk0; sY[bi * 512 + (16 + (lane & 15)) * 16 + il] = yk1; }
	v_pk_mul_f32 v[150:151], v[142:143], v[190:191]
	v_pk_fma_f32 v[150:151], v[144:145], v[198:199], v[150:151]
	v_pk_mul_f32 v[152:153], v[142:143], v[236:237]
	v_add_f32_e32 v154, v150, v151
	v_pk_fma_f32 v[152:153], v[144:145], v[238:239], v[152:153]
	v_pk_mul_f32 v[146:147], v[142:143], v[192:193]
	v_add_f32_dpp v154, v154, v154 quad_perm:[1,0,3,2] row_mask:0xf bank_mask:0xf bound_ctrl:1
	v_pk_mul_f32 v[148:149], v[144:145], v[200:201]
	v_add_f32_e32 v169, v152, v153
	v_add_f32_dpp v154, v154, v154 quad_perm:[2,3,0,1] row_mask:0xf bank_mask:0xf bound_ctrl:1
	v_pk_fma_f32 v[146:147], v[240:241], v[196:197], v[146:147] op_sel:[0,0,0] op_sel_hi:[0,1,1]
	v_pk_fma_f32 v[148:149], v[240:241], v[204:205], v[148:149] op_sel:[0,0,0] op_sel_hi:[0,1,1]
	v_add_f32_dpp v154, v154, v154 row_half_mirror row_mask:0xf bank_mask:0xf bound_ctrl:1
	s_nop 1
	v_add_f32_dpp v154, v154, v154 row_mirror row_mask:0xf bank_mask:0xf bound_ctrl:1
	v_pk_fma_f32 v[146:147], v[154:155], v[194:195], v[146:147] op_sel_hi:[0,1,1]
	v_pk_fma_f32 v[148:149], v[154:155], v[202:203], v[148:149] op_sel_hi:[0,1,1]
	s_waitcnt lgkmcnt(0)
	v_pk_mul_f32 v[150:151], v[146:147], v[206:207]
	v_pk_fma_f32 v[150:151], v[148:149], v[214:215], v[150:151]
	v_pk_mul_f32 v[152:153], v[146:147], v[228:229]
	v_add_f32_e32 v154, v150, v151
	v_pk_fma_f32 v[152:153], v[148:149], v[230:231], v[152:153]
	v_pk_mul_f32 v[142:143], v[146:147], v[208:209]
	v_add_f32_dpp v154, v154, v154 quad_perm:[1,0,3,2] row_mask:0xf bank_mask:0xf bound_ctrl:1
	v_pk_mul_f32 v[144:145], v[148:149], v[216:217]
	v_add_f32_e32 v170, v152, v153
	v_add_f32_dpp v154, v154, v154 quad_perm:[2,3,0,1] row_mask:0xf bank_mask:0xf bound_ctrl:1
	v_pk_fma_f32 v[142:143], v[240:241], v[212:213], v[142:143] op_sel:[1,0,0] op_sel_hi:[1,1,1]
	v_pk_fma_f32 v[144:145], v[240:241], v[220:221], v[144:145] op_sel:[1,0,0] op_sel_hi:[1,1,1]
	v_add_f32_dpp v154, v154, v154 row_half_mirror row_mask:0xf bank_mask:0xf bound_ctrl:1
	s_nop 1
	v_add_f32_dpp v154, v154, v154 row_mirror row_mask:0xf bank_mask:0xf bound_ctrl:1
	v_pk_fma_f32 v[142:143], v[154:155], v[210:211], v[142:143] op_sel_hi:[0,1,1]
	v_pk_fma_f32 v[144:145], v[154:155], v[218:219], v[144:145] op_sel_hi:[0,1,1]
	v_pk_mul_f32 v[152:153], v[142:143], v[232:233]
	v_pk_fma_f32 v[152:153], v[144:145], v[234:235], v[152:153]
	s_nop 0
	v_add_f32_e32 v171, v152, v153
	v_add_f32_dpp v172, v156, v156 row_ror:8 row_mask:0xf bank_mask:0x3
	v_add_f32_dpp v172, v164, v164 row_ror:8 row_mask:0xf bank_mask:0xc
	v_add_f32_dpp v173, v157, v157 row_ror:8 row_mask:0xf bank_mask:0x3
	v_add_f32_dpp v173, v165, v165 row_ror:8 row_mask:0xf bank_mask:0xc
	v_add_f32_dpp v174, v158, v158 row_ror:8 row_mask:0xf bank_mask:0x3
	v_add_f32_dpp v174, v166, v166 row_ror:8 row_mask:0xf bank_mask:0xc
	v_add_f32_dpp v175, v159, v159 row_ror:8 row_mask:0xf bank_mask:0x3
	v_add_f32_dpp v175, v167, v167 row_ror:8 row_mask:0xf bank_mask:0xc
	v_add_f32_dpp v176, v160, v160 row_ror:8 row_mask:0xf bank_mask:0x3
	v_add_f32_dpp v176, v168, v168 row_ror:8 row_mask:0xf bank_mask:0xc
	v_add_f32_dpp v177, v161, v161 row_ror:8 row_mask:0xf bank_mask:0x3
	v_add_f32_dpp v177, v169, v169 row_ror:8 row_mask:0xf bank_mask:0xc
	v_add_f32_dpp v178, v162, v162 row_ror:8 row_mask:0xf bank_mask:0x3
	v_add_f32_dpp v178, v170, v170 row_ror:8 row_mask:0xf bank_mask:0xc
	v_add_f32_dpp v179, v163, v163 row_ror:8 row_mask:0xf bank_mask:0x3
	v_add_f32_dpp v179, v171, v171 row_ror:8 row_mask:0xf bank_mask:0xc
	v_add_f32_dpp v156, v172, v172 row_half_mirror row_mask:0xf bank_mask:0x5
	v_add_f32_dpp v156, v176, v176 row_half_mirror row_mask:0xf bank_mask:0xa
	v_add_f32_dpp v157, v173, v173 row_half_mirror row_mask:0xf bank_mask:0x5
	v_add_f32_dpp v157, v177, v177 row_half_mirror row_mask:0xf bank_mask:0xa
	v_add_f32_dpp v158, v174, v174 row_half_mirror row_mask:0xf bank_mask:0x5
	v_add_f32_dpp v158, v178, v178 row_half_mirror row_mask:0xf bank_mask:0xa
	v_add_f32_dpp v159, v175, v175 row_half_mirror row_mask:0xf bank_mask:0x5
	v_add_f32_dpp v159, v179, v179 row_half_mirror row_mask:0xf bank_mask:0xa
	v_cndmask_b32_e64 v176, v158, v156, s[14:15]
	v_cndmask_b32_e64 v177, v159, v157, s[14:15]
	v_cndmask_b32_e64 v178, v156, v158, s[14:15]
	v_cndmask_b32_e64 v179, v157, v159, s[14:15]
	v_add_f32_dpp v172, v176, v178 quad_perm:[2,3,0,1] row_mask:0xf bank_mask:0xf
	v_add_f32_dpp v173, v177, v179 quad_perm:[2,3,0,1] row_mask:0xf bank_mask:0xf
	v_cndmask_b32_e64 v176, v173, v172, s[16:17]
	v_cndmask_b32_e64 v178, v172, v173, s[16:17]
	s_nop 0
	v_add_f32_dpp v181, v176, v178 quad_perm:[1,0,3,2] row_mask:0xf bank_mask:0xf
	ds_write2st64_b32 v187, v180, v181 offset0:8 offset1:12
